# removed the 32 mid-block s_setprio 0/1 toggle pairs between the two 16-MFMA halves of each GEMM super-phase (v087 otherwise)
# speedup vs baseline: 1.0011x; 1.0011x over previous
.LBB0_538:
	ds_read_b128 v[152:155], v149
	ds_read_b128 v[156:159], v149 offset:1024
	ds_read_b128 v[160:163], v149 offset:2048
	ds_read_b128 v[164:167], v149 offset:3072
	ds_read_b128 v[168:171], v150
	ds_read_b128 v[172:175], v150 offset:1024
	ds_read_b128 v[176:179], v150 offset:2048
	ds_read_b128 v[180:183], v150 offset:3072
	s_add_u32 s40, s38, 0xfffc0080
	s_addc_u32 s41, s39, -1
	s_cmp_eq_u32 s54, 12
	s_cselect_b32 s43, s27, s41
	s_cselect_b32 s42, s50, s40
	s_cselect_b32 s41, s25, s53
	s_cselect_b32 s40, s51, s52
	s_add_i32 m0, s11, 0xc000
	ds_read_b128 v[184:187], v151
	ds_read_b128 v[188:191], v151 offset:1024
	ds_read_b128 v[192:195], v151 offset:2048
	ds_read_b128 v[196:199], v151 offset:3072
	ds_read_b128 v[200:203], v151 offset:4096
	ds_read_b128 v[204:207], v151 offset:5120
	ds_read_b128 v[212:215], v151 offset:6144
	ds_read_b128 v[216:219], v151 offset:7168
	global_load_lds_dwordx4 v136, s[38:39]
	s_add_i32 m0, s11, 0xe000
	s_nop 0
	global_load_lds_dwordx4 v138, s[38:39]
	s_waitcnt vmcnt(8)
	s_waitcnt lgkmcnt(0)
	s_barrier
	s_setprio 1
	s_waitcnt lgkmcnt(0)
	v_mfma_f32_16x16x32_bf16 v[124:127], v[152:155], v[184:187], v[124:127]
	v_mfma_f32_16x16x32_bf16 v[120:123], v[160:163], v[184:187], v[120:123]
	v_mfma_f32_16x16x32_bf16 v[108:111], v[152:155], v[192:195], v[108:111]
	v_mfma_f32_16x16x32_bf16 v[104:107], v[160:163], v[192:195], v[104:107]
	v_mfma_f32_16x16x32_bf16 v[92:95], v[152:155], v[200:203], v[92:95]
	v_mfma_f32_16x16x32_bf16 v[88:91], v[160:163], v[200:203], v[88:91]
	v_mfma_f32_16x16x32_bf16 v[76:79], v[152:155], v[212:215], v[76:79]
	v_mfma_f32_16x16x32_bf16 v[72:75], v[160:163], v[212:215], v[72:75]
	v_mfma_f32_16x16x32_bf16 v[124:127], v[156:159], v[188:191], v[124:127]
	v_mfma_f32_16x16x32_bf16 v[120:123], v[164:167], v[188:191], v[120:123]
	v_mfma_f32_16x16x32_bf16 v[108:111], v[156:159], v[196:199], v[108:111]
	v_mfma_f32_16x16x32_bf16 v[104:107], v[164:167], v[196:199], v[104:107]
	v_mfma_f32_16x16x32_bf16 v[92:95], v[156:159], v[204:207], v[92:95]
	v_mfma_f32_16x16x32_bf16 v[88:91], v[164:167], v[204:207], v[88:91]
	v_mfma_f32_16x16x32_bf16 v[76:79], v[156:159], v[216:219], v[76:79]
	v_mfma_f32_16x16x32_bf16 v[72:75], v[164:167], v[216:219], v[72:75]
	v_mfma_f32_16x16x32_bf16 v[116:119], v[168:171], v[184:187], v[116:119]
	v_mfma_f32_16x16x32_bf16 v[112:115], v[176:179], v[184:187], v[112:115]
	v_mfma_f32_16x16x32_bf16 v[100:103], v[168:171], v[192:195], v[100:103]
	v_mfma_f32_16x16x32_bf16 v[96:99], v[176:179], v[192:195], v[96:99]
	v_mfma_f32_16x16x32_bf16 v[84:87], v[168:171], v[200:203], v[84:87]
	v_mfma_f32_16x16x32_bf16 v[80:83], v[176:179], v[200:203], v[80:83]
	v_mfma_f32_16x16x32_bf16 v[68:71], v[168:171], v[212:215], v[68:71]
	v_mfma_f32_16x16x32_bf16 v[64:67], v[176:179], v[212:215], v[64:67]
	v_mfma_f32_16x16x32_bf16 v[116:119], v[172:175], v[188:191], v[116:119]
	v_mfma_f32_16x16x32_bf16 v[112:115], v[180:183], v[188:191], v[112:115]
	v_mfma_f32_16x16x32_bf16 v[100:103], v[172:175], v[196:199], v[100:103]
	v_mfma_f32_16x16x32_bf16 v[96:99], v[180:183], v[196:199], v[96:99]
	v_mfma_f32_16x16x32_bf16 v[84:87], v[172:175], v[204:207], v[84:87]
	v_mfma_f32_16x16x32_bf16 v[80:83], v[180:183], v[204:207], v[80:83]
	v_mfma_f32_16x16x32_bf16 v[68:71], v[172:175], v[216:219], v[68:71]
	v_mfma_f32_16x16x32_bf16 v[64:67], v[180:183], v[216:219], v[64:67]
	s_setprio 0
	s_barrier
	s_add_i32 s55, s45, s10
	v_lshl_add_u64 v[144:145], s[40:41], 0, v[132:133]
	s_mov_b32 m0, s55
	ds_read_b128 v[184:187], v151 offset:16384
	ds_read_b128 v[188:191], v151 offset:17408
	ds_read_b128 v[192:195], v151 offset:18432
	ds_read_b128 v[196:199], v151 offset:19456
	ds_read_b128 v[200:203], v151 offset:20480
	ds_read_b128 v[204:207], v151 offset:21504
	ds_read_b128 v[212:215], v151 offset:22528
	ds_read_b128 v[216:219], v151 offset:23552
	global_load_lds_dwordx4 v[144:145], off
	s_add_i32 m0, s55, 0x2000
	s_add_u32 s56, s40, 0x40000
	v_lshl_add_u64 v[208:209], s[40:41], 0, v[128:129]
	s_addc_u32 s57, s41, 0
	s_add_i32 s55, s46, s10
	global_load_lds_dwordx4 v[208:209], off
	s_mov_b32 m0, s55
	v_lshl_add_u64 v[222:223], s[42:43], 0, v[130:131]
	global_load_lds_dwordx4 v132, s[56:57]
	s_add_i32 m0, s55, 0x2000
	s_nop 0
	global_load_lds_dwordx4 v128, s[56:57]
	v_lshl_add_u64 v[220:221], s[42:43], 0, v[134:135]
	s_mov_b32 m0, s11
	s_nop 0
	global_load_lds_dwordx4 v[220:221], off
	s_mov_b32 m0, s14
	s_nop 0
	global_load_lds_dwordx4 v[222:223], off
	s_waitcnt vmcnt(8)
	s_waitcnt lgkmcnt(0)
	s_barrier
	s_setprio 1
	s_waitcnt lgkmcnt(0)
	v_mfma_f32_16x16x32_bf16 v[60:63], v[152:155], v[184:187], v[60:63]
	v_mfma_f32_16x16x32_bf16 v[56:59], v[160:163], v[184:187], v[56:59]
	v_mfma_f32_16x16x32_bf16 v[44:47], v[152:155], v[192:195], v[44:47]
	v_mfma_f32_16x16x32_bf16 v[40:43], v[160:163], v[192:195], v[40:43]
	v_mfma_f32_16x16x32_bf16 v[28:31], v[152:155], v[200:203], v[28:31]
	v_mfma_f32_16x16x32_bf16 v[24:27], v[160:163], v[200:203], v[24:27]
	v_mfma_f32_16x16x32_bf16 v[12:15], v[152:155], v[212:215], v[12:15]
	v_mfma_f32_16x16x32_bf16 v[8:11], v[160:163], v[212:215], v[8:11]
	v_mfma_f32_16x16x32_bf16 v[60:63], v[156:159], v[188:191], v[60:63]
	v_mfma_f32_16x16x32_bf16 v[56:59], v[164:167], v[188:191], v[56:59]
	v_mfma_f32_16x16x32_bf16 v[44:47], v[156:159], v[196:199], v[44:47]
	v_mfma_f32_16x16x32_bf16 v[40:43], v[164:167], v[196:199], v[40:43]
	v_mfma_f32_16x16x32_bf16 v[28:31], v[156:159], v[204:207], v[28:31]
	v_mfma_f32_16x16x32_bf16 v[24:27], v[164:167], v[204:207], v[24:27]
	v_mfma_f32_16x16x32_bf16 v[12:15], v[156:159], v[216:219], v[12:15]
	v_mfma_f32_16x16x32_bf16 v[8:11], v[164:167], v[216:219], v[8:11]
	v_mfma_f32_16x16x32_bf16 v[52:55], v[168:171], v[184:187], v[52:55]
	v_mfma_f32_16x16x32_bf16 v[48:51], v[176:179], v[184:187], v[48:51]
	v_mfma_f32_16x16x32_bf16 v[36:39], v[168:171], v[192:195], v[36:39]
	v_mfma_f32_16x16x32_bf16 v[32:35], v[176:179], v[192:195], v[32:35]
	v_mfma_f32_16x16x32_bf16 v[20:23], v[168:171], v[200:203], v[20:23]
	v_mfma_f32_16x16x32_bf16 v[16:19], v[176:179], v[200:203], v[16:19]
	v_mfma_f32_16x16x32_bf16 v[4:7], v[168:171], v[212:215], v[4:7]
	v_mfma_f32_16x16x32_bf16 v[0:3], v[176:179], v[212:215], v[0:3]
	v_mfma_f32_16x16x32_bf16 v[52:55], v[172:175], v[188:191], v[52:55]
	v_mfma_f32_16x16x32_bf16 v[48:51], v[180:183], v[188:191], v[48:51]
	v_mfma_f32_16x16x32_bf16 v[36:39], v[172:175], v[196:199], v[36:39]
	v_mfma_f32_16x16x32_bf16 v[32:35], v[180:183], v[196:199], v[32:35]
	v_mfma_f32_16x16x32_bf16 v[20:23], v[172:175], v[204:207], v[20:23]
	v_mfma_f32_16x16x32_bf16 v[16:19], v[180:183], v[204:207], v[16:19]
	v_mfma_f32_16x16x32_bf16 v[4:7], v[172:175], v[216:219], v[4:7]
	v_mfma_f32_16x16x32_bf16 v[0:3], v[180:183], v[216:219], v[0:3]
	s_setprio 0
	s_barrier
	s_add_i32 s55, 0, 0x18000
	s_add_i32 s56, 0, 0x1c000
	v_add_u32_e32 v164, s55, v147
	v_add_u32_e32 v180, s56, v147
	ds_read_b128 v[152:155], v164
	ds_read_b128 v[156:159], v164 offset:1024
	ds_read_b128 v[160:163], v164 offset:2048
	ds_read_b128 v[164:167], v164 offset:3072
	ds_read_b128 v[168:171], v180
	ds_read_b128 v[172:175], v180 offset:1024
	ds_read_b128 v[176:179], v180 offset:2048
	ds_read_b128 v[180:183], v180 offset:3072
	s_add_u32 s42, s42, 0x40000
	s_addc_u32 s43, s43, 0
	s_mov_b32 m0, s15
	ds_read_b128 v[184:187], v151 offset:32768
	ds_read_b128 v[188:191], v151 offset:33792
	ds_read_b128 v[192:195], v151 offset:34816
	ds_read_b128 v[196:199], v151 offset:35840
	ds_read_b128 v[200:203], v151 offset:36864
	ds_read_b128 v[204:207], v151 offset:37888
	ds_read_b128 v[212:215], v151 offset:38912
	ds_read_b128 v[216:219], v151 offset:39936
	global_load_lds_dwordx4 v134, s[42:43]
	s_mov_b32 m0, s28
	s_nop 0
	global_load_lds_dwordx4 v130, s[42:43]
	s_waitcnt vmcnt(8)
	s_waitcnt lgkmcnt(0)
	s_barrier
	s_setprio 1
	s_waitcnt lgkmcnt(0)
	v_mfma_f32_16x16x32_bf16 v[124:127], v[152:155], v[184:187], v[124:127]
	v_mfma_f32_16x16x32_bf16 v[120:123], v[160:163], v[184:187], v[120:123]
	v_mfma_f32_16x16x32_bf16 v[108:111], v[152:155], v[192:195], v[108:111]
	v_mfma_f32_16x16x32_bf16 v[104:107], v[160:163], v[192:195], v[104:107]
	v_mfma_f32_16x16x32_bf16 v[92:95], v[152:155], v[200:203], v[92:95]
	v_mfma_f32_16x16x32_bf16 v[88:91], v[160:163], v[200:203], v[88:91]
	v_mfma_f32_16x16x32_bf16 v[76:79], v[152:155], v[212:215], v[76:79]
	v_mfma_f32_16x16x32_bf16 v[72:75], v[160:163], v[212:215], v[72:75]
	v_mfma_f32_16x16x32_bf16 v[124:127], v[156:159], v[188:191], v[124:127]
	v_mfma_f32_16x16x32_bf16 v[120:123], v[164:167], v[188:191], v[120:123]
	v_mfma_f32_16x16x32_bf16 v[108:111], v[156:159], v[196:199], v[108:111]
	v_mfma_f32_16x16x32_bf16 v[104:107], v[164:167], v[196:199], v[104:107]
	v_mfma_f32_16x16x32_bf16 v[92:95], v[156:159], v[204:207], v[92:95]
	v_mfma_f32_16x16x32_bf16 v[88:91], v[164:167], v[204:207], v[88:91]
	v_mfma_f32_16x16x32_bf16 v[76:79], v[156:159], v[216:219], v[76:79]
	v_mfma_f32_16x16x32_bf16 v[72:75], v[164:167], v[216:219], v[72:75]
	v_mfma_f32_16x16x32_bf16 v[116:119], v[168:171], v[184:187], v[116:119]
	v_mfma_f32_16x16x32_bf16 v[112:115], v[176:179], v[184:187], v[112:115]
	v_mfma_f32_16x16x32_bf16 v[100:103], v[168:171], v[192:195], v[100:103]
	v_mfma_f32_16x16x32_bf16 v[96:99], v[176:179], v[192:195], v[96:99]
	v_mfma_f32_16x16x32_bf16 v[84:87], v[168:171], v[200:203], v[84:87]
	v_mfma_f32_16x16x32_bf16 v[80:83], v[176:179], v[200:203], v[80:83]
	v_mfma_f32_16x16x32_bf16 v[68:71], v[168:171], v[212:215], v[68:71]
	v_mfma_f32_16x16x32_bf16 v[64:67], v[176:179], v[212:215], v[64:67]
	v_mfma_f32_16x16x32_bf16 v[116:119], v[172:175], v[188:191], v[116:119]
	v_mfma_f32_16x16x32_bf16 v[112:115], v[180:183], v[188:191], v[112:115]
	v_mfma_f32_16x16x32_bf16 v[100:103], v[172:175], v[196:199], v[100:103]
	v_mfma_f32_16x16x32_bf16 v[96:99], v[180:183], v[196:199], v[96:99]
	v_mfma_f32_16x16x32_bf16 v[84:87], v[172:175], v[204:207], v[84:87]
	v_mfma_f32_16x16x32_bf16 v[80:83], v[180:183], v[204:207], v[80:83]
	v_mfma_f32_16x16x32_bf16 v[68:71], v[172:175], v[216:219], v[68:71]
	v_mfma_f32_16x16x32_bf16 v[64:67], v[180:183], v[216:219], v[64:67]
	s_setprio 0
	s_barrier
	s_add_i32 s42, s55, s10
	v_lshl_add_u64 v[144:145], v[144:145], 0, s[4:5]
	s_mov_b32 m0, s42
	ds_read_b128 v[184:187], v151 offset:49152
	ds_read_b128 v[188:191], v151 offset:50176
	ds_read_b128 v[192:195], v151 offset:51200
	ds_read_b128 v[196:199], v151 offset:52224
	ds_read_b128 v[200:203], v151 offset:53248
	ds_read_b128 v[204:207], v151 offset:54272
	ds_read_b128 v[212:215], v151 offset:55296
	ds_read_b128 v[216:219], v151 offset:56320
	global_load_lds_dwordx4 v[144:145], off
	s_add_i32 m0, s42, 0x2000
	s_add_u32 s40, s40, 0x40080
	v_lshl_add_u64 v[144:145], v[208:209], 0, s[4:5]
	s_addc_u32 s41, s41, 0
	s_add_i32 s42, s56, s10
	global_load_lds_dwordx4 v[144:145], off
	s_mov_b32 m0, s42
	s_nop 0
	global_load_lds_dwordx4 v132, s[40:41]
	s_add_i32 m0, s42, 0x2000
	s_nop 0
	global_load_lds_dwordx4 v128, s[40:41]
	v_lshl_add_u64 v[144:145], v[220:221], 0, s[4:5]
	s_mov_b32 m0, s29
	s_nop 0
	global_load_lds_dwordx4 v[144:145], off
	v_lshl_add_u64 v[144:145], v[222:223], 0, s[4:5]
	s_mov_b32 m0, s33
	s_nop 0
	global_load_lds_dwordx4 v[144:145], off
	s_waitcnt vmcnt(8)
	s_waitcnt lgkmcnt(0)
	s_barrier
	s_setprio 1
	s_waitcnt lgkmcnt(0)
	v_mfma_f32_16x16x32_bf16 v[60:63], v[152:155], v[184:187], v[60:63]
	v_mfma_f32_16x16x32_bf16 v[56:59], v[160:163], v[184:187], v[56:59]
	v_mfma_f32_16x16x32_bf16 v[44:47], v[152:155], v[192:195], v[44:47]
	v_mfma_f32_16x16x32_bf16 v[40:43], v[160:163], v[192:195], v[40:43]
	v_mfma_f32_16x16x32_bf16 v[28:31], v[152:155], v[200:203], v[28:31]
	v_mfma_f32_16x16x32_bf16 v[24:27], v[160:163], v[200:203], v[24:27]
	v_mfma_f32_16x16x32_bf16 v[12:15], v[152:155], v[212:215], v[12:15]
	v_mfma_f32_16x16x32_bf16 v[8:11], v[160:163], v[212:215], v[8:11]
	v_mfma_f32_16x16x32_bf16 v[60:63], v[156:159], v[188:191], v[60:63]
	v_mfma_f32_16x16x32_bf16 v[56:59], v[164:167], v[188:191], v[56:59]
	v_mfma_f32_16x16x32_bf16 v[44:47], v[156:159], v[196:199], v[44:47]
	v_mfma_f32_16x16x32_bf16 v[40:43], v[164:167], v[196:199], v[40:43]
	v_mfma_f32_16x16x32_bf16 v[28:31], v[156:159], v[204:207], v[28:31]
	v_mfma_f32_16x16x32_bf16 v[24:27], v[164:167], v[204:207], v[24:27]
	v_mfma_f32_16x16x32_bf16 v[12:15], v[156:159], v[216:219], v[12:15]
	v_mfma_f32_16x16x32_bf16 v[8:11], v[164:167], v[216:219], v[8:11]
	v_mfma_f32_16x16x32_bf16 v[52:55], v[168:171], v[184:187], v[52:55]
	v_mfma_f32_16x16x32_bf16 v[48:51], v[176:179], v[184:187], v[48:51]
	v_mfma_f32_16x16x32_bf16 v[36:39], v[168:171], v[192:195], v[36:39]
	v_mfma_f32_16x16x32_bf16 v[32:35], v[176:179], v[192:195], v[32:35]
	v_mfma_f32_16x16x32_bf16 v[20:23], v[168:171], v[200:203], v[20:23]
	v_mfma_f32_16x16x32_bf16 v[16:19], v[176:179], v[200:203], v[16:19]
	v_mfma_f32_16x16x32_bf16 v[4:7], v[168:171], v[212:215], v[4:7]
	v_mfma_f32_16x16x32_bf16 v[0:3], v[176:179], v[212:215], v[0:3]
	v_mfma_f32_16x16x32_bf16 v[52:55], v[172:175], v[188:191], v[52:55]
	v_mfma_f32_16x16x32_bf16 v[48:51], v[180:183], v[188:191], v[48:51]
	v_mfma_f32_16x16x32_bf16 v[36:39], v[172:175], v[196:199], v[36:39]
	v_mfma_f32_16x16x32_bf16 v[32:35], v[180:183], v[196:199], v[32:35]
	v_mfma_f32_16x16x32_bf16 v[20:23], v[172:175], v[204:207], v[20:23]
	v_mfma_f32_16x16x32_bf16 v[16:19], v[180:183], v[204:207], v[16:19]
	v_mfma_f32_16x16x32_bf16 v[4:7], v[172:175], v[216:219], v[4:7]
	v_mfma_f32_16x16x32_bf16 v[0:3], v[180:183], v[216:219], v[0:3]
	s_setprio 0
	s_barrier
	s_add_i32 s54, s54, 2
	s_add_u32 s38, s38, 0x100
	s_addc_u32 s39, s39, 0
	s_add_u32 s52, s52, 0x100
	s_addc_u32 s53, s53, 0
	s_cmp_gt_u32 s54, 13
	s_cbranch_scc0 .LBB0_538
	s_and_b64 vcc, exec, s[8:9]
	s_cbranch_vccz .LBB0_541
	s_barrier

.LBB0_617:
	ds_read_b128 v[32:35], v186
	ds_read_b128 v[36:39], v186 offset:1024
	ds_read_b128 v[40:43], v186 offset:2048
	ds_read_b128 v[44:47], v186 offset:3072
	ds_read_b128 v[48:51], v187
	ds_read_b128 v[52:55], v187 offset:1024
	ds_read_b128 v[56:59], v187 offset:2048
	ds_read_b128 v[60:63], v187 offset:3072
	s_add_u32 s38, s2, 0x100
	s_addc_u32 s39, s3, 0
	s_cmp_eq_u32 s52, 40
	s_cselect_b32 s43, s7, s39
	s_cselect_b32 s42, s6, s38
	s_cselect_b32 s41, s37, s51
	s_cselect_b32 s40, s36, s1
	s_add_i32 m0, s11, 0xc000
	ds_read_b128 v[176:179], v188
	ds_read_b128 v[190:193], v188 offset:1024
	ds_read_b128 v[194:197], v188 offset:2048
	ds_read_b128 v[198:201], v188 offset:3072
	ds_read_b128 v[202:205], v188 offset:4096
	ds_read_b128 v[206:209], v188 offset:5120
	ds_read_b128 v[212:215], v188 offset:6144
	ds_read_b128 v[216:219], v188 offset:7168
	global_load_lds_dwordx4 v168, s[2:3]
	s_add_i32 m0, s11, 0xe000
	s_nop 0
	global_load_lds_dwordx4 v170, s[2:3]
	s_waitcnt vmcnt(8)
	s_waitcnt lgkmcnt(0)
	s_barrier
	s_setprio 1
	s_waitcnt lgkmcnt(0)
	v_mfma_f32_16x16x32_bf16 v[156:159], v[32:35], v[176:179], v[156:159]
	v_mfma_f32_16x16x32_bf16 v[152:155], v[40:43], v[176:179], v[152:155]
	v_mfma_f32_16x16x32_bf16 v[140:143], v[32:35], v[194:197], v[140:143]
	v_mfma_f32_16x16x32_bf16 v[136:139], v[40:43], v[194:197], v[136:139]
	v_mfma_f32_16x16x32_bf16 v[124:127], v[32:35], v[202:205], v[124:127]
	v_mfma_f32_16x16x32_bf16 v[120:123], v[40:43], v[202:205], v[120:123]
	v_mfma_f32_16x16x32_bf16 v[108:111], v[32:35], v[212:215], v[108:111]
	v_mfma_f32_16x16x32_bf16 v[104:107], v[40:43], v[212:215], v[104:107]
	v_mfma_f32_16x16x32_bf16 v[156:159], v[36:39], v[190:193], v[156:159]
	v_mfma_f32_16x16x32_bf16 v[152:155], v[44:47], v[190:193], v[152:155]
	v_mfma_f32_16x16x32_bf16 v[140:143], v[36:39], v[198:201], v[140:143]
	v_mfma_f32_16x16x32_bf16 v[136:139], v[44:47], v[198:201], v[136:139]
	v_mfma_f32_16x16x32_bf16 v[124:127], v[36:39], v[206:209], v[124:127]
	v_mfma_f32_16x16x32_bf16 v[120:123], v[44:47], v[206:209], v[120:123]
	v_mfma_f32_16x16x32_bf16 v[108:111], v[36:39], v[216:219], v[108:111]
	v_mfma_f32_16x16x32_bf16 v[104:107], v[44:47], v[216:219], v[104:107]
	v_mfma_f32_16x16x32_bf16 v[148:151], v[48:51], v[176:179], v[148:151]
	v_mfma_f32_16x16x32_bf16 v[144:147], v[56:59], v[176:179], v[144:147]
	v_mfma_f32_16x16x32_bf16 v[132:135], v[48:51], v[194:197], v[132:135]
	v_mfma_f32_16x16x32_bf16 v[128:131], v[56:59], v[194:197], v[128:131]
	v_mfma_f32_16x16x32_bf16 v[116:119], v[48:51], v[202:205], v[116:119]
	v_mfma_f32_16x16x32_bf16 v[112:115], v[56:59], v[202:205], v[112:115]
	v_mfma_f32_16x16x32_bf16 v[100:103], v[48:51], v[212:215], v[100:103]
	v_mfma_f32_16x16x32_bf16 v[96:99], v[56:59], v[212:215], v[96:99]
	v_mfma_f32_16x16x32_bf16 v[148:151], v[52:55], v[190:193], v[148:151]
	v_mfma_f32_16x16x32_bf16 v[144:147], v[60:63], v[190:193], v[144:147]
	v_mfma_f32_16x16x32_bf16 v[132:135], v[52:55], v[198:201], v[132:135]
	v_mfma_f32_16x16x32_bf16 v[128:131], v[60:63], v[198:201], v[128:131]
	v_mfma_f32_16x16x32_bf16 v[116:119], v[52:55], v[206:209], v[116:119]
	v_mfma_f32_16x16x32_bf16 v[112:115], v[60:63], v[206:209], v[112:115]
	v_mfma_f32_16x16x32_bf16 v[100:103], v[52:55], v[216:219], v[100:103]
	v_mfma_f32_16x16x32_bf16 v[96:99], v[60:63], v[216:219], v[96:99]
	s_setprio 0
	s_barrier
	s_add_i32 s2, s46, s10
	v_lshl_add_u64 v[180:181], s[40:41], 0, v[162:163]
	s_mov_b32 m0, s2
	ds_read_b128 v[176:179], v188 offset:16384
	ds_read_b128 v[190:193], v188 offset:17408
	ds_read_b128 v[194:197], v188 offset:18432
	ds_read_b128 v[198:201], v188 offset:19456
	ds_read_b128 v[202:205], v188 offset:20480
	ds_read_b128 v[206:209], v188 offset:21504
	ds_read_b128 v[212:215], v188 offset:22528
	ds_read_b128 v[216:219], v188 offset:23552
	global_load_lds_dwordx4 v[180:181], off
	s_add_i32 m0, s2, 0x2000
	s_add_u32 s2, s40, 0xb0000
	v_lshl_add_u64 v[228:229], s[40:41], 0, v[166:167]
	s_addc_u32 s3, s41, 0
	s_add_i32 s53, s47, s10
	global_load_lds_dwordx4 v[228:229], off
	s_mov_b32 m0, s53
	v_lshl_add_u64 v[230:231], s[42:43], 0, v[160:161]
	global_load_lds_dwordx4 v162, s[2:3]
	s_add_i32 m0, s53, 0x2000
	v_lshl_add_u64 v[232:233], s[42:43], 0, v[164:165]
	global_load_lds_dwordx4 v166, s[2:3]
	s_mov_b32 m0, s11
	s_nop 0
	global_load_lds_dwordx4 v[230:231], off
	s_mov_b32 m0, s14
	s_nop 0
	global_load_lds_dwordx4 v[232:233], off
	s_waitcnt vmcnt(8)
	s_waitcnt lgkmcnt(0)
	s_barrier
	s_setprio 1
	s_waitcnt lgkmcnt(0)
	v_mfma_f32_16x16x32_bf16 v[92:95], v[32:35], v[176:179], v[92:95]
	v_mfma_f32_16x16x32_bf16 v[88:91], v[40:43], v[176:179], v[88:91]
	v_mfma_f32_16x16x32_bf16 v[76:79], v[32:35], v[194:197], v[76:79]
	v_mfma_f32_16x16x32_bf16 v[72:75], v[40:43], v[194:197], v[72:75]
	v_mfma_f32_16x16x32_bf16 v[28:31], v[32:35], v[202:205], v[28:31]
	v_mfma_f32_16x16x32_bf16 v[24:27], v[40:43], v[202:205], v[24:27]
	v_mfma_f32_16x16x32_bf16 v[12:15], v[32:35], v[212:215], v[12:15]
	v_mfma_f32_16x16x32_bf16 v[8:11], v[40:43], v[212:215], v[8:11]
	v_mfma_f32_16x16x32_bf16 v[92:95], v[36:39], v[190:193], v[92:95]
	v_mfma_f32_16x16x32_bf16 v[88:91], v[44:47], v[190:193], v[88:91]
	v_mfma_f32_16x16x32_bf16 v[76:79], v[36:39], v[198:201], v[76:79]
	v_mfma_f32_16x16x32_bf16 v[72:75], v[44:47], v[198:201], v[72:75]
	v_mfma_f32_16x16x32_bf16 v[28:31], v[36:39], v[206:209], v[28:31]
	v_mfma_f32_16x16x32_bf16 v[24:27], v[44:47], v[206:209], v[24:27]
	v_mfma_f32_16x16x32_bf16 v[12:15], v[36:39], v[216:219], v[12:15]
	v_mfma_f32_16x16x32_bf16 v[8:11], v[44:47], v[216:219], v[8:11]
	v_mfma_f32_16x16x32_bf16 v[20:23], v[48:51], v[202:205], v[20:23]
	v_mfma_f32_16x16x32_bf16 v[16:19], v[56:59], v[202:205], v[16:19]
	v_mfma_f32_16x16x32_bf16 v[4:7], v[48:51], v[212:215], v[4:7]
	v_mfma_f32_16x16x32_bf16 v[0:3], v[56:59], v[212:215], v[0:3]
	v_mfma_f32_16x16x32_bf16 v[32:35], v[48:51], v[176:179], v[84:87]
	v_mfma_f32_16x16x32_bf16 v[36:39], v[56:59], v[176:179], v[80:83]
	v_mfma_f32_16x16x32_bf16 v[40:43], v[48:51], v[194:197], v[68:71]
	v_mfma_f32_16x16x32_bf16 v[44:47], v[56:59], v[194:197], v[64:67]
	v_mfma_f32_16x16x32_bf16 v[20:23], v[52:55], v[206:209], v[20:23]
	v_mfma_f32_16x16x32_bf16 v[16:19], v[60:63], v[206:209], v[16:19]
	v_mfma_f32_16x16x32_bf16 v[4:7], v[52:55], v[216:219], v[4:7]
	v_mfma_f32_16x16x32_bf16 v[0:3], v[60:63], v[216:219], v[0:3]
	v_mfma_f32_16x16x32_bf16 v[32:35], v[52:55], v[190:193], v[32:35]
	v_mfma_f32_16x16x32_bf16 v[36:39], v[60:63], v[190:193], v[36:39]
	v_mfma_f32_16x16x32_bf16 v[40:43], v[52:55], v[198:201], v[40:43]
	v_mfma_f32_16x16x32_bf16 v[44:47], v[60:63], v[198:201], v[44:47]
	s_setprio 0
	s_barrier
	s_add_i32 s53, 0, 0x18000
	s_add_i32 s54, 0, 0x1c000
	v_add_u32_e32 v60, s53, v183
	v_add_u32_e32 v64, s54, v183
	ds_read_b128 v[48:51], v60
	ds_read_b128 v[52:55], v60 offset:1024
	ds_read_b128 v[56:59], v60 offset:2048
	ds_read_b128 v[60:63], v60 offset:3072
	ds_read_b128 v[176:179], v64
	ds_read_b128 v[190:193], v64 offset:1024
	ds_read_b128 v[194:197], v64 offset:2048
	ds_read_b128 v[198:201], v64 offset:3072
	s_add_u32 s2, s42, 0xb0000
	s_addc_u32 s3, s43, 0
	s_mov_b32 m0, s15
	ds_read_b128 v[64:67], v188 offset:32768
	ds_read_b128 v[68:71], v188 offset:33792
	ds_read_b128 v[80:83], v188 offset:34816
	ds_read_b128 v[84:87], v188 offset:35840
	ds_read_b128 v[202:205], v188 offset:36864
	ds_read_b128 v[206:209], v188 offset:37888
	ds_read_b128 v[212:215], v188 offset:38912
	ds_read_b128 v[216:219], v188 offset:39936
	global_load_lds_dwordx4 v160, s[2:3]
	s_mov_b32 m0, s28
	s_nop 0
	global_load_lds_dwordx4 v164, s[2:3]
	s_waitcnt vmcnt(8)
	s_waitcnt lgkmcnt(0)
	s_barrier
	s_setprio 1
	s_waitcnt lgkmcnt(0)
	v_mfma_f32_16x16x32_bf16 v[156:159], v[48:51], v[64:67], v[156:159]
	v_mfma_f32_16x16x32_bf16 v[152:155], v[56:59], v[64:67], v[152:155]
	v_mfma_f32_16x16x32_bf16 v[140:143], v[48:51], v[80:83], v[140:143]
	v_mfma_f32_16x16x32_bf16 v[136:139], v[56:59], v[80:83], v[136:139]
	v_mfma_f32_16x16x32_bf16 v[124:127], v[48:51], v[202:205], v[124:127]
	v_mfma_f32_16x16x32_bf16 v[120:123], v[56:59], v[202:205], v[120:123]
	v_mfma_f32_16x16x32_bf16 v[108:111], v[48:51], v[212:215], v[108:111]
	v_mfma_f32_16x16x32_bf16 v[104:107], v[56:59], v[212:215], v[104:107]
	v_mfma_f32_16x16x32_bf16 v[156:159], v[52:55], v[68:71], v[156:159]
	v_mfma_f32_16x16x32_bf16 v[152:155], v[60:63], v[68:71], v[152:155]
	v_mfma_f32_16x16x32_bf16 v[140:143], v[52:55], v[84:87], v[140:143]
	v_mfma_f32_16x16x32_bf16 v[136:139], v[60:63], v[84:87], v[136:139]
	v_mfma_f32_16x16x32_bf16 v[124:127], v[52:55], v[206:209], v[124:127]
	v_mfma_f32_16x16x32_bf16 v[120:123], v[60:63], v[206:209], v[120:123]
	v_mfma_f32_16x16x32_bf16 v[108:111], v[52:55], v[216:219], v[108:111]
	v_mfma_f32_16x16x32_bf16 v[104:107], v[60:63], v[216:219], v[104:107]
	v_mfma_f32_16x16x32_bf16 v[148:151], v[176:179], v[64:67], v[148:151]
	v_mfma_f32_16x16x32_bf16 v[64:67], v[194:197], v[64:67], v[144:147]
	v_mfma_f32_16x16x32_bf16 v[144:147], v[198:201], v[68:71], v[64:67]
	v_mfma_f32_16x16x32_bf16 v[64:67], v[176:179], v[80:83], v[132:135]
	v_mfma_f32_16x16x32_bf16 v[132:135], v[190:193], v[84:87], v[64:67]
	v_mfma_f32_16x16x32_bf16 v[64:67], v[194:197], v[80:83], v[128:131]
	v_mfma_f32_16x16x32_bf16 v[128:131], v[198:201], v[84:87], v[64:67]
	v_mfma_f32_16x16x32_bf16 v[64:67], v[176:179], v[202:205], v[116:119]
	v_mfma_f32_16x16x32_bf16 v[116:119], v[190:193], v[206:209], v[64:67]
	v_mfma_f32_16x16x32_bf16 v[64:67], v[194:197], v[202:205], v[112:115]
	v_mfma_f32_16x16x32_bf16 v[112:115], v[198:201], v[206:209], v[64:67]
	v_mfma_f32_16x16x32_bf16 v[64:67], v[176:179], v[212:215], v[100:103]
	v_mfma_f32_16x16x32_bf16 v[100:103], v[190:193], v[216:219], v[64:67]
	v_mfma_f32_16x16x32_bf16 v[64:67], v[194:197], v[212:215], v[96:99]
	v_mfma_f32_16x16x32_bf16 v[148:151], v[190:193], v[68:71], v[148:151]
	v_mfma_f32_16x16x32_bf16 v[96:99], v[198:201], v[216:219], v[64:67]
	s_setprio 0
	s_barrier
	s_add_i32 s2, s53, s10
	v_lshl_add_u64 v[80:81], v[180:181], 0, s[26:27]
	s_mov_b32 m0, s2
	s_nop 0
	ds_read_b128 v[64:67], v188 offset:49152
	ds_read_b128 v[68:71], v188 offset:50176
	ds_read_b128 v[202:205], v188 offset:51200
	ds_read_b128 v[206:209], v188 offset:52224
	ds_read_b128 v[212:215], v188 offset:53248
	ds_read_b128 v[216:219], v188 offset:54272
	ds_read_b128 v[220:223], v188 offset:55296
	ds_read_b128 v[224:227], v188 offset:56320
	global_load_lds_dwordx4 v[80:81], off
	s_add_i32 m0, s2, 0x2000
	s_add_u32 s2, s40, 0xb0080
	v_lshl_add_u64 v[80:81], v[228:229], 0, s[26:27]
	s_addc_u32 s3, s41, 0
	s_add_i32 s40, s54, s10
	global_load_lds_dwordx4 v[80:81], off
	s_mov_b32 m0, s40
	s_nop 0
	global_load_lds_dwordx4 v162, s[2:3]
	s_add_i32 m0, s40, 0x2000
	s_nop 0
	global_load_lds_dwordx4 v166, s[2:3]
	v_lshl_add_u64 v[80:81], v[230:231], 0, s[26:27]
	s_mov_b32 m0, s33
	s_nop 0
	global_load_lds_dwordx4 v[80:81], off
	v_lshl_add_u64 v[80:81], v[232:233], 0, s[26:27]
	s_mov_b32 m0, s44
	s_nop 0
	global_load_lds_dwordx4 v[80:81], off
	s_waitcnt vmcnt(8)
	s_waitcnt lgkmcnt(0)
	s_barrier
	s_setprio 1
	s_waitcnt lgkmcnt(0)
	v_mfma_f32_16x16x32_bf16 v[80:83], v[48:51], v[64:67], v[92:95]
	v_mfma_f32_16x16x32_bf16 v[92:95], v[52:55], v[68:71], v[80:83]
	v_mfma_f32_16x16x32_bf16 v[80:83], v[56:59], v[64:67], v[88:91]
	v_mfma_f32_16x16x32_bf16 v[76:79], v[48:51], v[202:205], v[76:79]
	v_mfma_f32_16x16x32_bf16 v[72:75], v[56:59], v[202:205], v[72:75]
	v_mfma_f32_16x16x32_bf16 v[28:31], v[48:51], v[212:215], v[28:31]
	v_mfma_f32_16x16x32_bf16 v[24:27], v[56:59], v[212:215], v[24:27]
	v_mfma_f32_16x16x32_bf16 v[12:15], v[48:51], v[220:223], v[12:15]
	v_mfma_f32_16x16x32_bf16 v[8:11], v[56:59], v[220:223], v[8:11]
	v_mfma_f32_16x16x32_bf16 v[88:91], v[60:63], v[68:71], v[80:83]
	v_mfma_f32_16x16x32_bf16 v[76:79], v[52:55], v[206:209], v[76:79]
	v_mfma_f32_16x16x32_bf16 v[72:75], v[60:63], v[206:209], v[72:75]
	v_mfma_f32_16x16x32_bf16 v[28:31], v[52:55], v[216:219], v[28:31]
	v_mfma_f32_16x16x32_bf16 v[24:27], v[60:63], v[216:219], v[24:27]
	v_mfma_f32_16x16x32_bf16 v[12:15], v[52:55], v[224:227], v[12:15]
	v_mfma_f32_16x16x32_bf16 v[8:11], v[60:63], v[224:227], v[8:11]
	v_mfma_f32_16x16x32_bf16 v[32:35], v[176:179], v[64:67], v[32:35]
	v_mfma_f32_16x16x32_bf16 v[84:87], v[190:193], v[68:71], v[32:35]
	v_mfma_f32_16x16x32_bf16 v[32:35], v[194:197], v[64:67], v[36:39]
	v_mfma_f32_16x16x32_bf16 v[80:83], v[198:201], v[68:71], v[32:35]
	v_mfma_f32_16x16x32_bf16 v[32:35], v[176:179], v[202:205], v[40:43]
	v_mfma_f32_16x16x32_bf16 v[68:71], v[190:193], v[206:209], v[32:35]
	v_mfma_f32_16x16x32_bf16 v[32:35], v[194:197], v[202:205], v[44:47]
	v_mfma_f32_16x16x32_bf16 v[20:23], v[176:179], v[212:215], v[20:23]
	v_mfma_f32_16x16x32_bf16 v[16:19], v[194:197], v[212:215], v[16:19]
	v_mfma_f32_16x16x32_bf16 v[4:7], v[176:179], v[220:223], v[4:7]
	v_mfma_f32_16x16x32_bf16 v[0:3], v[194:197], v[220:223], v[0:3]
	v_mfma_f32_16x16x32_bf16 v[64:67], v[198:201], v[206:209], v[32:35]
	v_mfma_f32_16x16x32_bf16 v[20:23], v[190:193], v[216:219], v[20:23]
	v_mfma_f32_16x16x32_bf16 v[16:19], v[198:201], v[216:219], v[16:19]
	v_mfma_f32_16x16x32_bf16 v[4:7], v[190:193], v[224:227], v[4:7]
	v_mfma_f32_16x16x32_bf16 v[0:3], v[198:201], v[224:227], v[0:3]
	s_setprio 0
	s_barrier
	s_add_i32 s52, s52, 2
	s_add_u32 s1, s1, 0x100
	s_addc_u32 s51, s51, 0
	s_cmp_gt_u32 s52, 41
	s_mov_b64 s[2:3], s[38:39]
	s_cbranch_scc0 .LBB0_617
	s_and_b64 vcc, exec, s[34:35]
	s_cbranch_vccz .LBB0_620
	s_barrier

.LBB0_704:
	ds_read_b128 v[128:131], v214
	ds_read_b128 v[132:135], v214 offset:1024
	ds_read_b128 v[136:139], v214 offset:2048
	ds_read_b128 v[140:143], v214 offset:3072
	ds_read_b128 v[144:147], v215
	ds_read_b128 v[148:151], v215 offset:1024
	ds_read_b128 v[168:171], v215 offset:2048
	ds_read_b128 v[172:175], v215 offset:3072
	s_add_u32 s6, s4, 0xfffc0080
	s_addc_u32 s7, s5, -1
	s_cmp_eq_u32 s57, 12
	s_cselect_b32 s63, s3, s7
	s_cselect_b32 s62, s11, s6
	s_cselect_b32 s7, s14, s55
	s_cselect_b32 s6, s15, s28
	s_add_i32 m0, s64, 0xc000
	ds_read_b128 v[176:179], v216
	ds_read_b128 v[180:183], v216 offset:1024
	ds_read_b128 v[184:187], v216 offset:2048
	ds_read_b128 v[188:191], v216 offset:3072
	ds_read_b128 v[192:195], v216 offset:4096
	ds_read_b128 v[196:199], v216 offset:5120
	ds_read_b128 v[200:203], v216 offset:6144
	ds_read_b128 v[204:207], v216 offset:7168
	global_load_lds_dwordx4 v160, s[4:5]
	s_add_i32 m0, s64, 0xe000
	s_nop 0
	global_load_lds_dwordx4 v162, s[4:5]
	s_waitcnt vmcnt(8)
	s_waitcnt lgkmcnt(0)
	s_barrier
	s_setprio 1
	s_waitcnt lgkmcnt(0)
	v_mfma_f32_16x16x32_bf16 v[124:127], v[128:131], v[176:179], v[124:127]
	v_mfma_f32_16x16x32_bf16 v[120:123], v[136:139], v[176:179], v[120:123]
	v_mfma_f32_16x16x32_bf16 v[116:119], v[128:131], v[184:187], v[116:119]
	v_mfma_f32_16x16x32_bf16 v[112:115], v[136:139], v[184:187], v[112:115]
	v_mfma_f32_16x16x32_bf16 v[108:111], v[128:131], v[192:195], v[108:111]
	v_mfma_f32_16x16x32_bf16 v[100:103], v[136:139], v[192:195], v[100:103]
	v_mfma_f32_16x16x32_bf16 v[88:91], v[128:131], v[200:203], v[88:91]
	v_mfma_f32_16x16x32_bf16 v[80:83], v[136:139], v[200:203], v[80:83]
	v_mfma_f32_16x16x32_bf16 v[124:127], v[132:135], v[180:183], v[124:127]
	v_mfma_f32_16x16x32_bf16 v[120:123], v[140:143], v[180:183], v[120:123]
	v_mfma_f32_16x16x32_bf16 v[116:119], v[132:135], v[188:191], v[116:119]
	v_mfma_f32_16x16x32_bf16 v[112:115], v[140:143], v[188:191], v[112:115]
	v_mfma_f32_16x16x32_bf16 v[108:111], v[132:135], v[196:199], v[108:111]
	v_mfma_f32_16x16x32_bf16 v[100:103], v[140:143], v[196:199], v[100:103]
	v_mfma_f32_16x16x32_bf16 v[88:91], v[132:135], v[204:207], v[88:91]
	v_mfma_f32_16x16x32_bf16 v[80:83], v[140:143], v[204:207], v[80:83]
	v_mfma_f32_16x16x32_bf16 v[104:107], v[144:147], v[176:179], v[104:107]
	v_mfma_f32_16x16x32_bf16 v[96:99], v[168:171], v[176:179], v[96:99]
	v_mfma_f32_16x16x32_bf16 v[92:95], v[144:147], v[184:187], v[92:95]
	v_mfma_f32_16x16x32_bf16 v[84:87], v[168:171], v[184:187], v[84:87]
	v_mfma_f32_16x16x32_bf16 v[76:79], v[144:147], v[192:195], v[76:79]
	v_mfma_f32_16x16x32_bf16 v[72:75], v[168:171], v[192:195], v[72:75]
	v_mfma_f32_16x16x32_bf16 v[68:71], v[144:147], v[200:203], v[68:71]
	v_mfma_f32_16x16x32_bf16 v[64:67], v[168:171], v[200:203], v[64:67]
	v_mfma_f32_16x16x32_bf16 v[104:107], v[148:151], v[180:183], v[104:107]
	v_mfma_f32_16x16x32_bf16 v[96:99], v[172:175], v[180:183], v[96:99]
	v_mfma_f32_16x16x32_bf16 v[92:95], v[148:151], v[188:191], v[92:95]
	v_mfma_f32_16x16x32_bf16 v[84:87], v[172:175], v[188:191], v[84:87]
	v_mfma_f32_16x16x32_bf16 v[76:79], v[148:151], v[196:199], v[76:79]
	v_mfma_f32_16x16x32_bf16 v[72:75], v[172:175], v[196:199], v[72:75]
	v_mfma_f32_16x16x32_bf16 v[68:71], v[148:151], v[204:207], v[68:71]
	v_mfma_f32_16x16x32_bf16 v[64:67], v[172:175], v[204:207], v[64:67]
	s_setprio 0
	s_barrier
	s_add_i32 s68, s79, s33
	v_lshl_add_u64 v[208:209], s[6:7], 0, v[156:157]
	s_mov_b32 m0, s68
	ds_read_b128 v[176:179], v216 offset:16384
	ds_read_b128 v[180:183], v216 offset:17408
	ds_read_b128 v[184:187], v216 offset:18432
	ds_read_b128 v[188:191], v216 offset:19456
	ds_read_b128 v[192:195], v216 offset:20480
	ds_read_b128 v[196:199], v216 offset:21504
	ds_read_b128 v[200:203], v216 offset:22528
	ds_read_b128 v[204:207], v216 offset:23552
	global_load_lds_dwordx4 v[208:209], off
	s_add_i32 m0, s68, 0x2000
	s_add_u32 s84, s6, 0x40000
	v_lshl_add_u64 v[220:221], s[6:7], 0, v[152:153]
	s_addc_u32 s85, s7, 0
	s_add_i32 s68, s80, s33
	global_load_lds_dwordx4 v[220:221], off
	s_mov_b32 m0, s68
	v_lshl_add_u64 v[224:225], s[62:63], 0, v[154:155]
	global_load_lds_dwordx4 v156, s[84:85]
	s_add_i32 m0, s68, 0x2000
	s_nop 0
	global_load_lds_dwordx4 v152, s[84:85]
	v_lshl_add_u64 v[222:223], s[62:63], 0, v[158:159]
	s_mov_b32 m0, s64
	s_nop 0
	global_load_lds_dwordx4 v[222:223], off
	s_mov_b32 m0, s65
	s_nop 0
	global_load_lds_dwordx4 v[224:225], off
	s_waitcnt vmcnt(8)
	s_waitcnt lgkmcnt(0)
	s_barrier
	s_setprio 1
	s_waitcnt lgkmcnt(0)
	v_mfma_f32_16x16x32_bf16 v[60:63], v[128:131], v[176:179], v[60:63]
	v_mfma_f32_16x16x32_bf16 v[56:59], v[136:139], v[176:179], v[56:59]
	v_mfma_f32_16x16x32_bf16 v[52:55], v[128:131], v[184:187], v[52:55]
	v_mfma_f32_16x16x32_bf16 v[48:51], v[136:139], v[184:187], v[48:51]
	v_mfma_f32_16x16x32_bf16 v[40:43], v[128:131], v[192:195], v[40:43]
	v_mfma_f32_16x16x32_bf16 v[32:35], v[136:139], v[192:195], v[32:35]
	v_mfma_f32_16x16x32_bf16 v[20:23], v[128:131], v[200:203], v[20:23]
	v_mfma_f32_16x16x32_bf16 v[16:19], v[136:139], v[200:203], v[16:19]
	v_mfma_f32_16x16x32_bf16 v[60:63], v[132:135], v[180:183], v[60:63]
	v_mfma_f32_16x16x32_bf16 v[56:59], v[140:143], v[180:183], v[56:59]
	v_mfma_f32_16x16x32_bf16 v[52:55], v[132:135], v[188:191], v[52:55]
	v_mfma_f32_16x16x32_bf16 v[48:51], v[140:143], v[188:191], v[48:51]
	v_mfma_f32_16x16x32_bf16 v[40:43], v[132:135], v[196:199], v[40:43]
	v_mfma_f32_16x16x32_bf16 v[32:35], v[140:143], v[196:199], v[32:35]
	v_mfma_f32_16x16x32_bf16 v[20:23], v[132:135], v[204:207], v[20:23]
	v_mfma_f32_16x16x32_bf16 v[16:19], v[140:143], v[204:207], v[16:19]
	v_mfma_f32_16x16x32_bf16 v[44:47], v[144:147], v[176:179], v[44:47]
	v_mfma_f32_16x16x32_bf16 v[36:39], v[168:171], v[176:179], v[36:39]
	v_mfma_f32_16x16x32_bf16 v[28:31], v[144:147], v[184:187], v[28:31]
	v_mfma_f32_16x16x32_bf16 v[24:27], v[168:171], v[184:187], v[24:27]
	v_mfma_f32_16x16x32_bf16 v[12:15], v[144:147], v[192:195], v[12:15]
	v_mfma_f32_16x16x32_bf16 v[8:11], v[168:171], v[192:195], v[8:11]
	v_mfma_f32_16x16x32_bf16 v[4:7], v[144:147], v[200:203], v[4:7]
	v_mfma_f32_16x16x32_bf16 v[0:3], v[168:171], v[200:203], v[0:3]
	v_mfma_f32_16x16x32_bf16 v[44:47], v[148:151], v[180:183], v[44:47]
	v_mfma_f32_16x16x32_bf16 v[36:39], v[172:175], v[180:183], v[36:39]
	v_mfma_f32_16x16x32_bf16 v[28:31], v[148:151], v[188:191], v[28:31]
	v_mfma_f32_16x16x32_bf16 v[24:27], v[172:175], v[188:191], v[24:27]
	v_mfma_f32_16x16x32_bf16 v[12:15], v[148:151], v[196:199], v[12:15]
	v_mfma_f32_16x16x32_bf16 v[8:11], v[172:175], v[196:199], v[8:11]
	v_mfma_f32_16x16x32_bf16 v[4:7], v[148:151], v[204:207], v[4:7]
	v_mfma_f32_16x16x32_bf16 v[0:3], v[172:175], v[204:207], v[0:3]
	s_setprio 0
	s_barrier
	s_add_i32 s68, 0, 0x18000
	s_add_i32 s83, 0, 0x1c000
	v_add_u32_e32 v140, s68, v213
	v_add_u32_e32 v172, s83, v213
	ds_read_b128 v[128:131], v140
	ds_read_b128 v[132:135], v140 offset:1024
	ds_read_b128 v[136:139], v140 offset:2048
	ds_read_b128 v[140:143], v140 offset:3072
	ds_read_b128 v[144:147], v172
	ds_read_b128 v[148:151], v172 offset:1024
	ds_read_b128 v[168:171], v172 offset:2048
	ds_read_b128 v[172:175], v172 offset:3072
	s_add_u32 s62, s62, 0x40000
	s_addc_u32 s63, s63, 0
	s_mov_b32 m0, s66
	ds_read_b128 v[176:179], v216 offset:32768
	ds_read_b128 v[180:183], v216 offset:33792
	ds_read_b128 v[184:187], v216 offset:34816
	ds_read_b128 v[188:191], v216 offset:35840
	ds_read_b128 v[192:195], v216 offset:36864
	ds_read_b128 v[196:199], v216 offset:37888
	ds_read_b128 v[200:203], v216 offset:38912
	ds_read_b128 v[204:207], v216 offset:39936
	global_load_lds_dwordx4 v158, s[62:63]
	s_mov_b32 m0, s67
	s_nop 0
	global_load_lds_dwordx4 v154, s[62:63]
	s_waitcnt vmcnt(8)
	s_waitcnt lgkmcnt(0)
	s_barrier
	s_setprio 1
	s_waitcnt lgkmcnt(0)
	v_mfma_f32_16x16x32_bf16 v[124:127], v[128:131], v[176:179], v[124:127]
	v_mfma_f32_16x16x32_bf16 v[120:123], v[136:139], v[176:179], v[120:123]
	v_mfma_f32_16x16x32_bf16 v[116:119], v[128:131], v[184:187], v[116:119]
	v_mfma_f32_16x16x32_bf16 v[112:115], v[136:139], v[184:187], v[112:115]
	v_mfma_f32_16x16x32_bf16 v[108:111], v[128:131], v[192:195], v[108:111]
	v_mfma_f32_16x16x32_bf16 v[100:103], v[136:139], v[192:195], v[100:103]
	v_mfma_f32_16x16x32_bf16 v[88:91], v[128:131], v[200:203], v[88:91]
	v_mfma_f32_16x16x32_bf16 v[80:83], v[136:139], v[200:203], v[80:83]
	v_mfma_f32_16x16x32_bf16 v[124:127], v[132:135], v[180:183], v[124:127]
	v_mfma_f32_16x16x32_bf16 v[120:123], v[140:143], v[180:183], v[120:123]
	v_mfma_f32_16x16x32_bf16 v[116:119], v[132:135], v[188:191], v[116:119]
	v_mfma_f32_16x16x32_bf16 v[112:115], v[140:143], v[188:191], v[112:115]
	v_mfma_f32_16x16x32_bf16 v[108:111], v[132:135], v[196:199], v[108:111]
	v_mfma_f32_16x16x32_bf16 v[100:103], v[140:143], v[196:199], v[100:103]
	v_mfma_f32_16x16x32_bf16 v[88:91], v[132:135], v[204:207], v[88:91]
	v_mfma_f32_16x16x32_bf16 v[80:83], v[140:143], v[204:207], v[80:83]
	v_mfma_f32_16x16x32_bf16 v[104:107], v[144:147], v[176:179], v[104:107]
	v_mfma_f32_16x16x32_bf16 v[96:99], v[168:171], v[176:179], v[96:99]
	v_mfma_f32_16x16x32_bf16 v[92:95], v[144:147], v[184:187], v[92:95]
	v_mfma_f32_16x16x32_bf16 v[84:87], v[168:171], v[184:187], v[84:87]
	v_mfma_f32_16x16x32_bf16 v[76:79], v[144:147], v[192:195], v[76:79]
	v_mfma_f32_16x16x32_bf16 v[72:75], v[168:171], v[192:195], v[72:75]
	v_mfma_f32_16x16x32_bf16 v[68:71], v[144:147], v[200:203], v[68:71]
	v_mfma_f32_16x16x32_bf16 v[64:67], v[168:171], v[200:203], v[64:67]
	v_mfma_f32_16x16x32_bf16 v[104:107], v[148:151], v[180:183], v[104:107]
	v_mfma_f32_16x16x32_bf16 v[96:99], v[172:175], v[180:183], v[96:99]
	v_mfma_f32_16x16x32_bf16 v[92:95], v[148:151], v[188:191], v[92:95]
	v_mfma_f32_16x16x32_bf16 v[84:87], v[172:175], v[188:191], v[84:87]
	v_mfma_f32_16x16x32_bf16 v[76:79], v[148:151], v[196:199], v[76:79]
	v_mfma_f32_16x16x32_bf16 v[72:75], v[172:175], v[196:199], v[72:75]
	v_mfma_f32_16x16x32_bf16 v[68:71], v[148:151], v[204:207], v[68:71]
	v_mfma_f32_16x16x32_bf16 v[64:67], v[172:175], v[204:207], v[64:67]
	s_setprio 0
	s_barrier
	s_add_i32 s62, s68, s33
	v_lshl_add_u64 v[208:209], v[208:209], 0, s[42:43]
	s_mov_b32 m0, s62
	ds_read_b128 v[176:179], v216 offset:49152
	ds_read_b128 v[180:183], v216 offset:50176
	ds_read_b128 v[184:187], v216 offset:51200
	ds_read_b128 v[188:191], v216 offset:52224
	ds_read_b128 v[192:195], v216 offset:53248
	ds_read_b128 v[196:199], v216 offset:54272
	ds_read_b128 v[200:203], v216 offset:55296
	ds_read_b128 v[204:207], v216 offset:56320
	global_load_lds_dwordx4 v[208:209], off
	s_add_i32 m0, s62, 0x2000
	s_add_u32 s6, s6, 0x40080
	v_lshl_add_u64 v[208:209], v[220:221], 0, s[42:43]
	s_addc_u32 s7, s7, 0
	s_add_i32 s62, s83, s33
	global_load_lds_dwordx4 v[208:209], off
	s_mov_b32 m0, s62
	s_nop 0
	global_load_lds_dwordx4 v156, s[6:7]
	s_add_i32 m0, s62, 0x2000
	s_nop 0
	global_load_lds_dwordx4 v152, s[6:7]
	v_lshl_add_u64 v[208:209], v[222:223], 0, s[42:43]
	s_mov_b32 m0, s75
	s_nop 0
	global_load_lds_dwordx4 v[208:209], off
	v_lshl_add_u64 v[208:209], v[224:225], 0, s[42:43]
	s_mov_b32 m0, s76
	s_nop 0
	global_load_lds_dwordx4 v[208:209], off
	s_waitcnt vmcnt(8)
	s_waitcnt lgkmcnt(0)
	s_barrier
	s_setprio 1
	s_waitcnt lgkmcnt(0)
	v_mfma_f32_16x16x32_bf16 v[60:63], v[128:131], v[176:179], v[60:63]
	v_mfma_f32_16x16x32_bf16 v[56:59], v[136:139], v[176:179], v[56:59]
	v_mfma_f32_16x16x32_bf16 v[52:55], v[128:131], v[184:187], v[52:55]
	v_mfma_f32_16x16x32_bf16 v[48:51], v[136:139], v[184:187], v[48:51]
	v_mfma_f32_16x16x32_bf16 v[40:43], v[128:131], v[192:195], v[40:43]
	v_mfma_f32_16x16x32_bf16 v[32:35], v[136:139], v[192:195], v[32:35]
	v_mfma_f32_16x16x32_bf16 v[20:23], v[128:131], v[200:203], v[20:23]
	v_mfma_f32_16x16x32_bf16 v[16:19], v[136:139], v[200:203], v[16:19]
	v_mfma_f32_16x16x32_bf16 v[60:63], v[132:135], v[180:183], v[60:63]
	v_mfma_f32_16x16x32_bf16 v[56:59], v[140:143], v[180:183], v[56:59]
	v_mfma_f32_16x16x32_bf16 v[52:55], v[132:135], v[188:191], v[52:55]
	v_mfma_f32_16x16x32_bf16 v[48:51], v[140:143], v[188:191], v[48:51]
	v_mfma_f32_16x16x32_bf16 v[40:43], v[132:135], v[196:199], v[40:43]
	v_mfma_f32_16x16x32_bf16 v[32:35], v[140:143], v[196:199], v[32:35]
	v_mfma_f32_16x16x32_bf16 v[20:23], v[132:135], v[204:207], v[20:23]
	v_mfma_f32_16x16x32_bf16 v[16:19], v[140:143], v[204:207], v[16:19]
	v_mfma_f32_16x16x32_bf16 v[44:47], v[144:147], v[176:179], v[44:47]
	v_mfma_f32_16x16x32_bf16 v[36:39], v[168:171], v[176:179], v[36:39]
	v_mfma_f32_16x16x32_bf16 v[28:31], v[144:147], v[184:187], v[28:31]
	v_mfma_f32_16x16x32_bf16 v[24:27], v[168:171], v[184:187], v[24:27]
	v_mfma_f32_16x16x32_bf16 v[12:15], v[144:147], v[192:195], v[12:15]
	v_mfma_f32_16x16x32_bf16 v[8:11], v[168:171], v[192:195], v[8:11]
	v_mfma_f32_16x16x32_bf16 v[4:7], v[144:147], v[200:203], v[4:7]
	v_mfma_f32_16x16x32_bf16 v[0:3], v[168:171], v[200:203], v[0:3]
	v_mfma_f32_16x16x32_bf16 v[44:47], v[148:151], v[180:183], v[44:47]
	v_mfma_f32_16x16x32_bf16 v[36:39], v[172:175], v[180:183], v[36:39]
	v_mfma_f32_16x16x32_bf16 v[28:31], v[148:151], v[188:191], v[28:31]
	v_mfma_f32_16x16x32_bf16 v[24:27], v[172:175], v[188:191], v[24:27]
	v_mfma_f32_16x16x32_bf16 v[12:15], v[148:151], v[196:199], v[12:15]
	v_mfma_f32_16x16x32_bf16 v[8:11], v[172:175], v[196:199], v[8:11]
	v_mfma_f32_16x16x32_bf16 v[4:7], v[148:151], v[204:207], v[4:7]
	v_mfma_f32_16x16x32_bf16 v[0:3], v[172:175], v[204:207], v[0:3]
	s_setprio 0
	s_barrier
	s_add_i32 s57, s57, 2
	s_add_u32 s4, s4, 0x100
	s_addc_u32 s5, s5, 0
	s_add_u32 s28, s28, 0x100
	s_addc_u32 s55, s55, 0
	s_cmp_gt_u32 s57, 13
	s_cbranch_scc0 .LBB0_704
	s_and_b64 vcc, exec, s[44:45]
	s_cbranch_vccz .LBB0_707
	s_barrier

.LBB0_862:
	ds_read_b128 v[152:155], v159
	ds_read_b128 v[164:167], v159 offset:1024
	ds_read_b128 v[168:171], v159 offset:2048
	ds_read_b128 v[172:175], v159 offset:3072
	ds_read_b128 v[176:179], v160
	ds_read_b128 v[180:183], v160 offset:1024
	ds_read_b128 v[184:187], v160 offset:2048
	ds_read_b128 v[188:191], v160 offset:3072
	s_add_u32 s4, s40, 0x100
	s_addc_u32 s5, s41, 0
	s_cmp_eq_u32 s58, 2
	s_cselect_b32 s45, s35, s5
	s_cselect_b32 s44, s34, s4
	s_cselect_b32 s43, s37, s57
	s_cselect_b32 s42, s36, s56
	s_add_i32 m0, s11, 0xc000
	ds_read_b128 v[192:195], v161
	ds_read_b128 v[196:199], v161 offset:1024
	ds_read_b128 v[200:203], v161 offset:2048
	ds_read_b128 v[204:207], v161 offset:3072
	ds_read_b128 v[212:215], v161 offset:4096
	ds_read_b128 v[216:219], v161 offset:5120
	ds_read_b128 v[220:223], v161 offset:6144
	ds_read_b128 v[224:227], v161 offset:7168
	global_load_lds_dwordx4 v144, s[40:41]
	s_add_i32 m0, s11, 0xe000
	s_nop 0
	global_load_lds_dwordx4 v146, s[40:41]
	s_waitcnt vmcnt(8)
	s_waitcnt lgkmcnt(0)
	s_barrier
	s_setprio 1
	s_waitcnt lgkmcnt(0)
	v_mfma_f32_16x16x32_bf16 v[124:127], v[152:155], v[192:195], v[124:127]
	v_mfma_f32_16x16x32_bf16 v[120:123], v[168:171], v[192:195], v[120:123]
	v_mfma_f32_16x16x32_bf16 v[108:111], v[152:155], v[200:203], v[108:111]
	v_mfma_f32_16x16x32_bf16 v[104:107], v[168:171], v[200:203], v[104:107]
	v_mfma_f32_16x16x32_bf16 v[92:95], v[152:155], v[212:215], v[92:95]
	v_mfma_f32_16x16x32_bf16 v[88:91], v[168:171], v[212:215], v[88:91]
	v_mfma_f32_16x16x32_bf16 v[76:79], v[152:155], v[220:223], v[76:79]
	v_mfma_f32_16x16x32_bf16 v[72:75], v[168:171], v[220:223], v[72:75]
	v_mfma_f32_16x16x32_bf16 v[124:127], v[164:167], v[196:199], v[124:127]
	v_mfma_f32_16x16x32_bf16 v[120:123], v[172:175], v[196:199], v[120:123]
	v_mfma_f32_16x16x32_bf16 v[108:111], v[164:167], v[204:207], v[108:111]
	v_mfma_f32_16x16x32_bf16 v[104:107], v[172:175], v[204:207], v[104:107]
	v_mfma_f32_16x16x32_bf16 v[92:95], v[164:167], v[216:219], v[92:95]
	v_mfma_f32_16x16x32_bf16 v[88:91], v[172:175], v[216:219], v[88:91]
	v_mfma_f32_16x16x32_bf16 v[76:79], v[164:167], v[224:227], v[76:79]
	v_mfma_f32_16x16x32_bf16 v[72:75], v[172:175], v[224:227], v[72:75]
	v_mfma_f32_16x16x32_bf16 v[116:119], v[176:179], v[192:195], v[116:119]
	v_mfma_f32_16x16x32_bf16 v[112:115], v[184:187], v[192:195], v[112:115]
	v_mfma_f32_16x16x32_bf16 v[100:103], v[176:179], v[200:203], v[100:103]
	v_mfma_f32_16x16x32_bf16 v[96:99], v[184:187], v[200:203], v[96:99]
	v_mfma_f32_16x16x32_bf16 v[84:87], v[176:179], v[212:215], v[84:87]
	v_mfma_f32_16x16x32_bf16 v[80:83], v[184:187], v[212:215], v[80:83]
	v_mfma_f32_16x16x32_bf16 v[68:71], v[176:179], v[220:223], v[68:71]
	v_mfma_f32_16x16x32_bf16 v[64:67], v[184:187], v[220:223], v[64:67]
	v_mfma_f32_16x16x32_bf16 v[116:119], v[180:183], v[196:199], v[116:119]
	v_mfma_f32_16x16x32_bf16 v[112:115], v[188:191], v[196:199], v[112:115]
	v_mfma_f32_16x16x32_bf16 v[100:103], v[180:183], v[204:207], v[100:103]
	v_mfma_f32_16x16x32_bf16 v[96:99], v[188:191], v[204:207], v[96:99]
	v_mfma_f32_16x16x32_bf16 v[84:87], v[180:183], v[216:219], v[84:87]
	v_mfma_f32_16x16x32_bf16 v[80:83], v[188:191], v[216:219], v[80:83]
	v_mfma_f32_16x16x32_bf16 v[68:71], v[180:183], v[224:227], v[68:71]
	v_mfma_f32_16x16x32_bf16 v[64:67], v[188:191], v[224:227], v[64:67]
	s_setprio 0
	s_barrier
	s_add_i32 s40, s48, s10
	v_lshl_add_u64 v[156:157], s[42:43], 0, v[130:131]
	s_mov_b32 m0, s40
	ds_read_b128 v[192:195], v161 offset:16384
	ds_read_b128 v[196:199], v161 offset:17408
	ds_read_b128 v[200:203], v161 offset:18432
	ds_read_b128 v[204:207], v161 offset:19456
	ds_read_b128 v[212:215], v161 offset:20480
	ds_read_b128 v[216:219], v161 offset:21504
	ds_read_b128 v[220:223], v161 offset:22528
	ds_read_b128 v[224:227], v161 offset:23552
	global_load_lds_dwordx4 v[156:157], off
	s_add_i32 m0, s40, 0x2000
	s_add_u32 s40, s42, 0x18000
	v_lshl_add_u64 v[208:209], s[42:43], 0, v[134:135]
	s_addc_u32 s41, s43, 0
	s_add_i32 s59, s49, s10
	global_load_lds_dwordx4 v[208:209], off
	s_mov_b32 m0, s59
	v_lshl_add_u64 v[230:231], s[44:45], 0, v[132:133]
	global_load_lds_dwordx4 v130, s[40:41]
	s_add_i32 m0, s59, 0x2000
	s_nop 0
	global_load_lds_dwordx4 v134, s[40:41]
	v_lshl_add_u64 v[228:229], s[44:45], 0, v[128:129]
	s_mov_b32 m0, s11
	s_nop 0
	global_load_lds_dwordx4 v[228:229], off
	s_mov_b32 m0, s14
	s_nop 0
	global_load_lds_dwordx4 v[230:231], off
	s_waitcnt vmcnt(8)
	s_waitcnt lgkmcnt(0)
	s_barrier
	s_setprio 1
	s_waitcnt lgkmcnt(0)
	v_mfma_f32_16x16x32_bf16 v[60:63], v[152:155], v[192:195], v[60:63]
	v_mfma_f32_16x16x32_bf16 v[56:59], v[168:171], v[192:195], v[56:59]
	v_mfma_f32_16x16x32_bf16 v[44:47], v[152:155], v[200:203], v[44:47]
	v_mfma_f32_16x16x32_bf16 v[40:43], v[168:171], v[200:203], v[40:43]
	v_mfma_f32_16x16x32_bf16 v[28:31], v[152:155], v[212:215], v[28:31]
	v_mfma_f32_16x16x32_bf16 v[24:27], v[168:171], v[212:215], v[24:27]
	v_mfma_f32_16x16x32_bf16 v[12:15], v[152:155], v[220:223], v[12:15]
	v_mfma_f32_16x16x32_bf16 v[8:11], v[168:171], v[220:223], v[8:11]
	v_mfma_f32_16x16x32_bf16 v[60:63], v[164:167], v[196:199], v[60:63]
	v_mfma_f32_16x16x32_bf16 v[56:59], v[172:175], v[196:199], v[56:59]
	v_mfma_f32_16x16x32_bf16 v[44:47], v[164:167], v[204:207], v[44:47]
	v_mfma_f32_16x16x32_bf16 v[40:43], v[172:175], v[204:207], v[40:43]
	v_mfma_f32_16x16x32_bf16 v[28:31], v[164:167], v[216:219], v[28:31]
	v_mfma_f32_16x16x32_bf16 v[24:27], v[172:175], v[216:219], v[24:27]
	v_mfma_f32_16x16x32_bf16 v[12:15], v[164:167], v[224:227], v[12:15]
	v_mfma_f32_16x16x32_bf16 v[8:11], v[172:175], v[224:227], v[8:11]
	v_mfma_f32_16x16x32_bf16 v[52:55], v[176:179], v[192:195], v[52:55]
	v_mfma_f32_16x16x32_bf16 v[48:51], v[184:187], v[192:195], v[48:51]
	v_mfma_f32_16x16x32_bf16 v[36:39], v[176:179], v[200:203], v[36:39]
	v_mfma_f32_16x16x32_bf16 v[32:35], v[184:187], v[200:203], v[32:35]
	v_mfma_f32_16x16x32_bf16 v[20:23], v[176:179], v[212:215], v[20:23]
	v_mfma_f32_16x16x32_bf16 v[16:19], v[184:187], v[212:215], v[16:19]
	v_mfma_f32_16x16x32_bf16 v[4:7], v[176:179], v[220:223], v[4:7]
	v_mfma_f32_16x16x32_bf16 v[0:3], v[184:187], v[220:223], v[0:3]
	v_mfma_f32_16x16x32_bf16 v[52:55], v[180:183], v[196:199], v[52:55]
	v_mfma_f32_16x16x32_bf16 v[48:51], v[188:191], v[196:199], v[48:51]
	v_mfma_f32_16x16x32_bf16 v[36:39], v[180:183], v[204:207], v[36:39]
	v_mfma_f32_16x16x32_bf16 v[32:35], v[188:191], v[204:207], v[32:35]
	v_mfma_f32_16x16x32_bf16 v[20:23], v[180:183], v[216:219], v[20:23]
	v_mfma_f32_16x16x32_bf16 v[16:19], v[188:191], v[216:219], v[16:19]
	v_mfma_f32_16x16x32_bf16 v[4:7], v[180:183], v[224:227], v[4:7]
	v_mfma_f32_16x16x32_bf16 v[0:3], v[188:191], v[224:227], v[0:3]
	s_setprio 0
	s_barrier
	s_add_i32 s59, 0, 0x18000
	v_add_u32_e32 v163, s59, v158
	s_add_i32 s60, 0, 0x1c000
	ds_read_b128 v[152:155], v163
	ds_read_b128 v[164:167], v163 offset:1024
	ds_read_b128 v[168:171], v163 offset:2048
	ds_read_b128 v[172:175], v163 offset:3072
	v_add_u32_e32 v163, s60, v158
	ds_read_b128 v[176:179], v163
	ds_read_b128 v[180:183], v163 offset:1024
	ds_read_b128 v[184:187], v163 offset:2048
	ds_read_b128 v[188:191], v163 offset:3072
	s_add_u32 s40, s44, 0x18000
	s_addc_u32 s41, s45, 0
	s_mov_b32 m0, s15
	ds_read_b128 v[192:195], v161 offset:32768
	ds_read_b128 v[196:199], v161 offset:33792
	ds_read_b128 v[200:203], v161 offset:34816
	ds_read_b128 v[204:207], v161 offset:35840
	ds_read_b128 v[212:215], v161 offset:36864
	ds_read_b128 v[216:219], v161 offset:37888
	ds_read_b128 v[220:223], v161 offset:38912
	ds_read_b128 v[224:227], v161 offset:39936
	global_load_lds_dwordx4 v128, s[40:41]
	s_mov_b32 m0, s28
	s_nop 0
	global_load_lds_dwordx4 v132, s[40:41]
	s_waitcnt vmcnt(8)
	s_waitcnt lgkmcnt(0)
	s_barrier
	s_setprio 1
	s_waitcnt lgkmcnt(0)
	v_mfma_f32_16x16x32_bf16 v[124:127], v[152:155], v[192:195], v[124:127]
	v_mfma_f32_16x16x32_bf16 v[120:123], v[168:171], v[192:195], v[120:123]
	v_mfma_f32_16x16x32_bf16 v[108:111], v[152:155], v[200:203], v[108:111]
	v_mfma_f32_16x16x32_bf16 v[104:107], v[168:171], v[200:203], v[104:107]
	v_mfma_f32_16x16x32_bf16 v[92:95], v[152:155], v[212:215], v[92:95]
	v_mfma_f32_16x16x32_bf16 v[88:91], v[168:171], v[212:215], v[88:91]
	v_mfma_f32_16x16x32_bf16 v[76:79], v[152:155], v[220:223], v[76:79]
	v_mfma_f32_16x16x32_bf16 v[72:75], v[168:171], v[220:223], v[72:75]
	v_mfma_f32_16x16x32_bf16 v[124:127], v[164:167], v[196:199], v[124:127]
	v_mfma_f32_16x16x32_bf16 v[120:123], v[172:175], v[196:199], v[120:123]
	v_mfma_f32_16x16x32_bf16 v[108:111], v[164:167], v[204:207], v[108:111]
	v_mfma_f32_16x16x32_bf16 v[104:107], v[172:175], v[204:207], v[104:107]
	v_mfma_f32_16x16x32_bf16 v[92:95], v[164:167], v[216:219], v[92:95]
	v_mfma_f32_16x16x32_bf16 v[88:91], v[172:175], v[216:219], v[88:91]
	v_mfma_f32_16x16x32_bf16 v[76:79], v[164:167], v[224:227], v[76:79]
	v_mfma_f32_16x16x32_bf16 v[72:75], v[172:175], v[224:227], v[72:75]
	v_mfma_f32_16x16x32_bf16 v[116:119], v[176:179], v[192:195], v[116:119]
	v_mfma_f32_16x16x32_bf16 v[112:115], v[184:187], v[192:195], v[112:115]
	v_mfma_f32_16x16x32_bf16 v[100:103], v[176:179], v[200:203], v[100:103]
	v_mfma_f32_16x16x32_bf16 v[96:99], v[184:187], v[200:203], v[96:99]
	v_mfma_f32_16x16x32_bf16 v[84:87], v[176:179], v[212:215], v[84:87]
	v_mfma_f32_16x16x32_bf16 v[80:83], v[184:187], v[212:215], v[80:83]
	v_mfma_f32_16x16x32_bf16 v[68:71], v[176:179], v[220:223], v[68:71]
	v_mfma_f32_16x16x32_bf16 v[64:67], v[184:187], v[220:223], v[64:67]
	v_mfma_f32_16x16x32_bf16 v[116:119], v[180:183], v[196:199], v[116:119]
	v_mfma_f32_16x16x32_bf16 v[112:115], v[188:191], v[196:199], v[112:115]
	v_mfma_f32_16x16x32_bf16 v[100:103], v[180:183], v[204:207], v[100:103]
	v_mfma_f32_16x16x32_bf16 v[96:99], v[188:191], v[204:207], v[96:99]
	v_mfma_f32_16x16x32_bf16 v[84:87], v[180:183], v[216:219], v[84:87]
	v_mfma_f32_16x16x32_bf16 v[80:83], v[188:191], v[216:219], v[80:83]
	v_mfma_f32_16x16x32_bf16 v[68:71], v[180:183], v[224:227], v[68:71]
	v_mfma_f32_16x16x32_bf16 v[64:67], v[188:191], v[224:227], v[64:67]
	s_setprio 0
	s_barrier
	s_add_i32 s40, s59, s10
	v_lshl_add_u64 v[156:157], v[156:157], 0, s[8:9]
	s_mov_b32 m0, s40
	ds_read_b128 v[192:195], v161 offset:49152
	ds_read_b128 v[196:199], v161 offset:50176
	ds_read_b128 v[200:203], v161 offset:51200
	ds_read_b128 v[204:207], v161 offset:52224
	ds_read_b128 v[212:215], v161 offset:53248
	ds_read_b128 v[216:219], v161 offset:54272
	ds_read_b128 v[220:223], v161 offset:55296
	ds_read_b128 v[224:227], v161 offset:56320
	global_load_lds_dwordx4 v[156:157], off
	s_add_i32 m0, s40, 0x2000
	s_add_u32 s40, s42, 0x18080
	v_lshl_add_u64 v[156:157], v[208:209], 0, s[8:9]
	s_addc_u32 s41, s43, 0
	s_add_i32 s42, s60, s10
	global_load_lds_dwordx4 v[156:157], off
	s_mov_b32 m0, s42
	s_nop 0
	global_load_lds_dwordx4 v130, s[40:41]
	s_add_i32 m0, s42, 0x2000
	s_nop 0
	global_load_lds_dwordx4 v134, s[40:41]
	v_lshl_add_u64 v[156:157], v[228:229], 0, s[8:9]
	s_mov_b32 m0, s33
	s_nop 0
	global_load_lds_dwordx4 v[156:157], off
	v_lshl_add_u64 v[156:157], v[230:231], 0, s[8:9]
	s_mov_b32 m0, s46
	s_nop 0
	global_load_lds_dwordx4 v[156:157], off
	s_waitcnt vmcnt(8)
	s_waitcnt lgkmcnt(0)
	s_barrier
	s_setprio 1
	s_waitcnt lgkmcnt(0)
	v_mfma_f32_16x16x32_bf16 v[60:63], v[152:155], v[192:195], v[60:63]
	v_mfma_f32_16x16x32_bf16 v[56:59], v[168:171], v[192:195], v[56:59]
	v_mfma_f32_16x16x32_bf16 v[44:47], v[152:155], v[200:203], v[44:47]
	v_mfma_f32_16x16x32_bf16 v[40:43], v[168:171], v[200:203], v[40:43]
	v_mfma_f32_16x16x32_bf16 v[28:31], v[152:155], v[212:215], v[28:31]
	v_mfma_f32_16x16x32_bf16 v[24:27], v[168:171], v[212:215], v[24:27]
	v_mfma_f32_16x16x32_bf16 v[12:15], v[152:155], v[220:223], v[12:15]
	v_mfma_f32_16x16x32_bf16 v[8:11], v[168:171], v[220:223], v[8:11]
	v_mfma_f32_16x16x32_bf16 v[60:63], v[164:167], v[196:199], v[60:63]
	v_mfma_f32_16x16x32_bf16 v[56:59], v[172:175], v[196:199], v[56:59]
	v_mfma_f32_16x16x32_bf16 v[44:47], v[164:167], v[204:207], v[44:47]
	v_mfma_f32_16x16x32_bf16 v[40:43], v[172:175], v[204:207], v[40:43]
	v_mfma_f32_16x16x32_bf16 v[28:31], v[164:167], v[216:219], v[28:31]
	v_mfma_f32_16x16x32_bf16 v[24:27], v[172:175], v[216:219], v[24:27]
	v_mfma_f32_16x16x32_bf16 v[12:15], v[164:167], v[224:227], v[12:15]
	v_mfma_f32_16x16x32_bf16 v[8:11], v[172:175], v[224:227], v[8:11]
	v_mfma_f32_16x16x32_bf16 v[52:55], v[176:179], v[192:195], v[52:55]
	v_mfma_f32_16x16x32_bf16 v[48:51], v[184:187], v[192:195], v[48:51]
	v_mfma_f32_16x16x32_bf16 v[36:39], v[176:179], v[200:203], v[36:39]
	v_mfma_f32_16x16x32_bf16 v[32:35], v[184:187], v[200:203], v[32:35]
	v_mfma_f32_16x16x32_bf16 v[20:23], v[176:179], v[212:215], v[20:23]
	v_mfma_f32_16x16x32_bf16 v[16:19], v[184:187], v[212:215], v[16:19]
	v_mfma_f32_16x16x32_bf16 v[4:7], v[176:179], v[220:223], v[4:7]
	v_mfma_f32_16x16x32_bf16 v[0:3], v[184:187], v[220:223], v[0:3]
	v_mfma_f32_16x16x32_bf16 v[52:55], v[180:183], v[196:199], v[52:55]
	v_mfma_f32_16x16x32_bf16 v[48:51], v[188:191], v[196:199], v[48:51]
	v_mfma_f32_16x16x32_bf16 v[36:39], v[180:183], v[204:207], v[36:39]
	v_mfma_f32_16x16x32_bf16 v[32:35], v[188:191], v[204:207], v[32:35]
	v_mfma_f32_16x16x32_bf16 v[20:23], v[180:183], v[216:219], v[20:23]
	v_mfma_f32_16x16x32_bf16 v[16:19], v[188:191], v[216:219], v[16:19]
	v_mfma_f32_16x16x32_bf16 v[4:7], v[180:183], v[224:227], v[4:7]
	v_mfma_f32_16x16x32_bf16 v[0:3], v[188:191], v[224:227], v[0:3]
	s_setprio 0
	s_barrier
	s_add_i32 s58, s58, 2
	s_add_u32 s56, s56, 0x100
	s_addc_u32 s57, s57, 0
	s_cmp_gt_u32 s58, 3
	s_mov_b64 s[40:41], s[4:5]
	s_cbranch_scc0 .LBB0_862
	s_and_b64 vcc, exec, s[20:21]
	s_cbranch_vccz .LBB0_865
	s_barrier

.LBB0_894:
	s_add_u32 s46, s34, s40
	s_addc_u32 s47, s35, s41
	s_add_u32 s44, s46, 0x100
	s_addc_u32 s45, s47, 0
	s_and_b64 s[42:43], s[38:39], exec
	s_cselect_b32 s43, s19, s45
	s_cselect_b32 s42, s53, s44
	s_add_u32 s40, s30, s40
	s_addc_u32 s41, s31, s41
	s_add_u32 s40, s40, 0x100
	s_addc_u32 s41, s41, 0
	s_and_b64 s[38:39], s[38:39], exec
	s_cselect_b32 s45, s9, s41
	s_cselect_b32 s44, s54, s40
	s_add_u32 s48, s46, 0x10080
	ds_read_b128 v[144:147], v150
	ds_read_b128 v[154:157], v150 offset:1024
	ds_read_b128 v[158:161], v150 offset:2048
	ds_read_b128 v[162:165], v150 offset:3072
	ds_read_b128 v[166:169], v151
	ds_read_b128 v[170:173], v151 offset:1024
	ds_read_b128 v[174:177], v151 offset:2048
	ds_read_b128 v[178:181], v151 offset:3072
	s_addc_u32 s49, s47, 0
	s_add_i32 s64, s50, s10
	s_add_i32 m0, s11, 0xc000
	s_add_i32 s65, s11, 0xe000
	s_add_i32 s61, s64, 0x2000
	s_add_u32 s46, s44, 0x10000
	s_addc_u32 s47, s45, 0
	s_add_i32 s63, s51, s10
	s_add_i32 s62, s63, 0x2000
	s_add_i32 s60, 0, 0x18000
	s_add_i32 s59, 0, 0x1c000
	s_add_u32 s40, s42, 0x10000
	s_addc_u32 s41, s43, 0
	s_add_i32 s58, s60, s10
	s_add_i32 s56, s58, 0x2000
	s_add_u32 s38, s44, 0x10080
	s_addc_u32 s39, s45, 0
	s_add_i32 s57, s59, s10
	s_add_i32 s55, s57, 0x2000
	ds_read_b128 v[182:185], v152
	ds_read_b128 v[186:189], v152 offset:1024
	ds_read_b128 v[190:193], v152 offset:2048
	ds_read_b128 v[194:197], v152 offset:3072
	ds_read_b128 v[198:201], v152 offset:4096
	ds_read_b128 v[202:205], v152 offset:5120
	ds_read_b128 v[206:209], v152 offset:6144
	ds_read_b128 v[212:215], v152 offset:7168
	global_load_lds_dwordx4 v134, s[48:49]
	s_mov_b32 m0, s65
	s_nop 0
	global_load_lds_dwordx4 v130, s[48:49]
	s_waitcnt vmcnt(8)
	s_waitcnt lgkmcnt(0)
	s_barrier
	s_setprio 1
	s_waitcnt lgkmcnt(0)
	v_mfma_f32_16x16x32_bf16 v[124:127], v[144:147], v[182:185], v[124:127]
	v_mfma_f32_16x16x32_bf16 v[120:123], v[158:161], v[182:185], v[120:123]
	v_mfma_f32_16x16x32_bf16 v[108:111], v[144:147], v[190:193], v[108:111]
	v_mfma_f32_16x16x32_bf16 v[104:107], v[158:161], v[190:193], v[104:107]
	v_mfma_f32_16x16x32_bf16 v[92:95], v[144:147], v[198:201], v[92:95]
	v_mfma_f32_16x16x32_bf16 v[88:91], v[158:161], v[198:201], v[88:91]
	v_mfma_f32_16x16x32_bf16 v[76:79], v[144:147], v[206:209], v[76:79]
	v_mfma_f32_16x16x32_bf16 v[72:75], v[158:161], v[206:209], v[72:75]
	v_mfma_f32_16x16x32_bf16 v[124:127], v[154:157], v[186:189], v[124:127]
	v_mfma_f32_16x16x32_bf16 v[120:123], v[162:165], v[186:189], v[120:123]
	v_mfma_f32_16x16x32_bf16 v[108:111], v[154:157], v[194:197], v[108:111]
	v_mfma_f32_16x16x32_bf16 v[104:107], v[162:165], v[194:197], v[104:107]
	v_mfma_f32_16x16x32_bf16 v[92:95], v[154:157], v[202:205], v[92:95]
	v_mfma_f32_16x16x32_bf16 v[88:91], v[162:165], v[202:205], v[88:91]
	v_mfma_f32_16x16x32_bf16 v[76:79], v[154:157], v[212:215], v[76:79]
	v_mfma_f32_16x16x32_bf16 v[72:75], v[162:165], v[212:215], v[72:75]
	v_mfma_f32_16x16x32_bf16 v[116:119], v[166:169], v[182:185], v[116:119]
	v_mfma_f32_16x16x32_bf16 v[112:115], v[174:177], v[182:185], v[112:115]
	v_mfma_f32_16x16x32_bf16 v[100:103], v[166:169], v[190:193], v[100:103]
	v_mfma_f32_16x16x32_bf16 v[96:99], v[174:177], v[190:193], v[96:99]
	v_mfma_f32_16x16x32_bf16 v[84:87], v[166:169], v[198:201], v[84:87]
	v_mfma_f32_16x16x32_bf16 v[80:83], v[174:177], v[198:201], v[80:83]
	v_mfma_f32_16x16x32_bf16 v[68:71], v[166:169], v[206:209], v[68:71]
	v_mfma_f32_16x16x32_bf16 v[64:67], v[174:177], v[206:209], v[64:67]
	v_mfma_f32_16x16x32_bf16 v[116:119], v[170:173], v[186:189], v[116:119]
	v_mfma_f32_16x16x32_bf16 v[112:115], v[178:181], v[186:189], v[112:115]
	v_mfma_f32_16x16x32_bf16 v[100:103], v[170:173], v[194:197], v[100:103]
	v_mfma_f32_16x16x32_bf16 v[96:99], v[178:181], v[194:197], v[96:99]
	v_mfma_f32_16x16x32_bf16 v[84:87], v[170:173], v[202:205], v[84:87]
	v_mfma_f32_16x16x32_bf16 v[80:83], v[178:181], v[202:205], v[80:83]
	v_mfma_f32_16x16x32_bf16 v[68:71], v[170:173], v[212:215], v[68:71]
	v_mfma_f32_16x16x32_bf16 v[64:67], v[178:181], v[212:215], v[64:67]
	s_setprio 0
	s_barrier
	s_mov_b32 m0, s64
	v_lshl_add_u64 v[216:217], s[44:45], 0, v[132:133]
	ds_read_b128 v[182:185], v152 offset:16384
	ds_read_b128 v[186:189], v152 offset:17408
	ds_read_b128 v[190:193], v152 offset:18432
	ds_read_b128 v[194:197], v152 offset:19456
	ds_read_b128 v[198:201], v152 offset:20480
	ds_read_b128 v[202:205], v152 offset:21504
	ds_read_b128 v[206:209], v152 offset:22528
	ds_read_b128 v[212:215], v152 offset:23552
	global_load_lds_dwordx4 v[216:217], off
	v_lshl_add_u64 v[218:219], s[44:45], 0, v[128:129]
	s_mov_b32 m0, s61
	s_nop 0
	global_load_lds_dwordx4 v[218:219], off
	s_mov_b32 m0, s63
	v_lshl_add_u64 v[222:223], s[42:43], 0, v[130:131]
	global_load_lds_dwordx4 v132, s[46:47]
	s_mov_b32 m0, s62
	s_nop 0
	global_load_lds_dwordx4 v128, s[46:47]
	v_lshl_add_u64 v[220:221], s[42:43], 0, v[134:135]
	s_mov_b32 m0, s11
	s_nop 0
	global_load_lds_dwordx4 v[220:221], off
	s_mov_b32 m0, s14
	s_nop 0
	global_load_lds_dwordx4 v[222:223], off
	s_waitcnt vmcnt(8)
	s_waitcnt lgkmcnt(0)
	s_barrier
	s_setprio 1
	s_waitcnt lgkmcnt(0)
	v_mfma_f32_16x16x32_bf16 v[60:63], v[144:147], v[182:185], v[60:63]
	v_mfma_f32_16x16x32_bf16 v[56:59], v[158:161], v[182:185], v[56:59]
	v_mfma_f32_16x16x32_bf16 v[44:47], v[144:147], v[190:193], v[44:47]
	v_mfma_f32_16x16x32_bf16 v[40:43], v[158:161], v[190:193], v[40:43]
	v_mfma_f32_16x16x32_bf16 v[28:31], v[144:147], v[198:201], v[28:31]
	v_mfma_f32_16x16x32_bf16 v[24:27], v[158:161], v[198:201], v[24:27]
	v_mfma_f32_16x16x32_bf16 v[12:15], v[144:147], v[206:209], v[12:15]
	v_mfma_f32_16x16x32_bf16 v[8:11], v[158:161], v[206:209], v[8:11]
	v_mfma_f32_16x16x32_bf16 v[60:63], v[154:157], v[186:189], v[60:63]
	v_mfma_f32_16x16x32_bf16 v[56:59], v[162:165], v[186:189], v[56:59]
	v_mfma_f32_16x16x32_bf16 v[44:47], v[154:157], v[194:197], v[44:47]
	v_mfma_f32_16x16x32_bf16 v[40:43], v[162:165], v[194:197], v[40:43]
	v_mfma_f32_16x16x32_bf16 v[28:31], v[154:157], v[202:205], v[28:31]
	v_mfma_f32_16x16x32_bf16 v[24:27], v[162:165], v[202:205], v[24:27]
	v_mfma_f32_16x16x32_bf16 v[12:15], v[154:157], v[212:215], v[12:15]
	v_mfma_f32_16x16x32_bf16 v[8:11], v[162:165], v[212:215], v[8:11]
	v_mfma_f32_16x16x32_bf16 v[52:55], v[166:169], v[182:185], v[52:55]
	v_mfma_f32_16x16x32_bf16 v[48:51], v[174:177], v[182:185], v[48:51]
	v_mfma_f32_16x16x32_bf16 v[36:39], v[166:169], v[190:193], v[36:39]
	v_mfma_f32_16x16x32_bf16 v[32:35], v[174:177], v[190:193], v[32:35]
	v_mfma_f32_16x16x32_bf16 v[20:23], v[166:169], v[198:201], v[20:23]
	v_mfma_f32_16x16x32_bf16 v[16:19], v[174:177], v[198:201], v[16:19]
	v_mfma_f32_16x16x32_bf16 v[4:7], v[166:169], v[206:209], v[4:7]
	v_mfma_f32_16x16x32_bf16 v[0:3], v[174:177], v[206:209], v[0:3]
	v_mfma_f32_16x16x32_bf16 v[52:55], v[170:173], v[186:189], v[52:55]
	v_mfma_f32_16x16x32_bf16 v[48:51], v[178:181], v[186:189], v[48:51]
	v_mfma_f32_16x16x32_bf16 v[36:39], v[170:173], v[194:197], v[36:39]
	v_mfma_f32_16x16x32_bf16 v[32:35], v[178:181], v[194:197], v[32:35]
	v_mfma_f32_16x16x32_bf16 v[20:23], v[170:173], v[202:205], v[20:23]
	v_mfma_f32_16x16x32_bf16 v[16:19], v[178:181], v[202:205], v[16:19]
	v_mfma_f32_16x16x32_bf16 v[4:7], v[170:173], v[212:215], v[4:7]
	v_mfma_f32_16x16x32_bf16 v[0:3], v[178:181], v[212:215], v[0:3]
	s_setprio 0
	s_barrier
	v_add_u32_e32 v162, s60, v149
	v_add_u32_e32 v178, s59, v149
	ds_read_b128 v[144:147], v162
	ds_read_b128 v[154:157], v162 offset:1024
	ds_read_b128 v[158:161], v162 offset:2048
	ds_read_b128 v[162:165], v162 offset:3072
	ds_read_b128 v[166:169], v178
	ds_read_b128 v[170:173], v178 offset:1024
	ds_read_b128 v[174:177], v178 offset:2048
	ds_read_b128 v[178:181], v178 offset:3072
	s_mov_b32 m0, s15
	ds_read_b128 v[182:185], v152 offset:32768
	ds_read_b128 v[186:189], v152 offset:33792
	ds_read_b128 v[190:193], v152 offset:34816
	ds_read_b128 v[194:197], v152 offset:35840
	ds_read_b128 v[198:201], v152 offset:36864
	ds_read_b128 v[202:205], v152 offset:37888
	ds_read_b128 v[206:209], v152 offset:38912
	ds_read_b128 v[212:215], v152 offset:39936
	global_load_lds_dwordx4 v134, s[40:41]
	s_mov_b32 m0, s27
	s_nop 0
	global_load_lds_dwordx4 v130, s[40:41]
	s_waitcnt vmcnt(8)
	s_waitcnt lgkmcnt(0)
	s_barrier
	s_setprio 1
	s_waitcnt lgkmcnt(0)
	v_mfma_f32_16x16x32_bf16 v[124:127], v[144:147], v[182:185], v[124:127]
	v_mfma_f32_16x16x32_bf16 v[120:123], v[158:161], v[182:185], v[120:123]
	v_mfma_f32_16x16x32_bf16 v[108:111], v[144:147], v[190:193], v[108:111]
	v_mfma_f32_16x16x32_bf16 v[104:107], v[158:161], v[190:193], v[104:107]
	v_mfma_f32_16x16x32_bf16 v[92:95], v[144:147], v[198:201], v[92:95]
	v_mfma_f32_16x16x32_bf16 v[88:91], v[158:161], v[198:201], v[88:91]
	v_mfma_f32_16x16x32_bf16 v[76:79], v[144:147], v[206:209], v[76:79]
	v_mfma_f32_16x16x32_bf16 v[72:75], v[158:161], v[206:209], v[72:75]
	v_mfma_f32_16x16x32_bf16 v[124:127], v[154:157], v[186:189], v[124:127]
	v_mfma_f32_16x16x32_bf16 v[120:123], v[162:165], v[186:189], v[120:123]
	v_mfma_f32_16x16x32_bf16 v[108:111], v[154:157], v[194:197], v[108:111]
	v_mfma_f32_16x16x32_bf16 v[104:107], v[162:165], v[194:197], v[104:107]
	v_mfma_f32_16x16x32_bf16 v[92:95], v[154:157], v[202:205], v[92:95]
	v_mfma_f32_16x16x32_bf16 v[88:91], v[162:165], v[202:205], v[88:91]
	v_mfma_f32_16x16x32_bf16 v[76:79], v[154:157], v[212:215], v[76:79]
	v_mfma_f32_16x16x32_bf16 v[72:75], v[162:165], v[212:215], v[72:75]
	v_mfma_f32_16x16x32_bf16 v[116:119], v[166:169], v[182:185], v[116:119]
	v_mfma_f32_16x16x32_bf16 v[112:115], v[174:177], v[182:185], v[112:115]
	v_mfma_f32_16x16x32_bf16 v[100:103], v[166:169], v[190:193], v[100:103]
	v_mfma_f32_16x16x32_bf16 v[96:99], v[174:177], v[190:193], v[96:99]
	v_mfma_f32_16x16x32_bf16 v[84:87], v[166:169], v[198:201], v[84:87]
	v_mfma_f32_16x16x32_bf16 v[80:83], v[174:177], v[198:201], v[80:83]
	v_mfma_f32_16x16x32_bf16 v[68:71], v[166:169], v[206:209], v[68:71]
	v_mfma_f32_16x16x32_bf16 v[64:67], v[174:177], v[206:209], v[64:67]
	v_mfma_f32_16x16x32_bf16 v[116:119], v[170:173], v[186:189], v[116:119]
	v_mfma_f32_16x16x32_bf16 v[112:115], v[178:181], v[186:189], v[112:115]
	v_mfma_f32_16x16x32_bf16 v[100:103], v[170:173], v[194:197], v[100:103]
	v_mfma_f32_16x16x32_bf16 v[96:99], v[178:181], v[194:197], v[96:99]
	v_mfma_f32_16x16x32_bf16 v[84:87], v[170:173], v[202:205], v[84:87]
	v_mfma_f32_16x16x32_bf16 v[80:83], v[178:181], v[202:205], v[80:83]
	v_mfma_f32_16x16x32_bf16 v[68:71], v[170:173], v[212:215], v[68:71]
	v_mfma_f32_16x16x32_bf16 v[64:67], v[178:181], v[212:215], v[64:67]
	s_setprio 0
	s_barrier
	s_mov_b32 m0, s58
	v_lshl_add_u64 v[216:217], v[216:217], 0, s[2:3]
	ds_read_b128 v[182:185], v152 offset:49152
	ds_read_b128 v[186:189], v152 offset:50176
	ds_read_b128 v[190:193], v152 offset:51200
	ds_read_b128 v[194:197], v152 offset:52224
	ds_read_b128 v[198:201], v152 offset:53248
	ds_read_b128 v[202:205], v152 offset:54272
	ds_read_b128 v[206:209], v152 offset:55296
	ds_read_b128 v[212:215], v152 offset:56320
	global_load_lds_dwordx4 v[216:217], off
	v_lshl_add_u64 v[216:217], v[218:219], 0, s[2:3]
	s_mov_b32 m0, s56
	s_nop 0
	global_load_lds_dwordx4 v[216:217], off
	s_mov_b32 m0, s57
	s_nop 0
	global_load_lds_dwordx4 v132, s[38:39]
	s_mov_b32 m0, s55
	s_nop 0
	global_load_lds_dwordx4 v128, s[38:39]
	v_lshl_add_u64 v[216:217], v[220:221], 0, s[2:3]
	s_mov_b32 m0, s29
	s_nop 0
	global_load_lds_dwordx4 v[216:217], off
	v_lshl_add_u64 v[216:217], v[222:223], 0, s[2:3]
	s_mov_b32 m0, s33
	s_nop 0
	global_load_lds_dwordx4 v[216:217], off
	s_waitcnt vmcnt(8)
	s_waitcnt lgkmcnt(0)
	s_barrier
	s_setprio 1
	s_waitcnt lgkmcnt(0)
	v_mfma_f32_16x16x32_bf16 v[60:63], v[144:147], v[182:185], v[60:63]
	v_mfma_f32_16x16x32_bf16 v[56:59], v[158:161], v[182:185], v[56:59]
	v_mfma_f32_16x16x32_bf16 v[44:47], v[144:147], v[190:193], v[44:47]
	v_mfma_f32_16x16x32_bf16 v[40:43], v[158:161], v[190:193], v[40:43]
	v_mfma_f32_16x16x32_bf16 v[28:31], v[144:147], v[198:201], v[28:31]
	v_mfma_f32_16x16x32_bf16 v[24:27], v[158:161], v[198:201], v[24:27]
	v_mfma_f32_16x16x32_bf16 v[12:15], v[144:147], v[206:209], v[12:15]
	v_mfma_f32_16x16x32_bf16 v[8:11], v[158:161], v[206:209], v[8:11]
	v_mfma_f32_16x16x32_bf16 v[60:63], v[154:157], v[186:189], v[60:63]
	v_mfma_f32_16x16x32_bf16 v[56:59], v[162:165], v[186:189], v[56:59]
	v_mfma_f32_16x16x32_bf16 v[44:47], v[154:157], v[194:197], v[44:47]
	v_mfma_f32_16x16x32_bf16 v[40:43], v[162:165], v[194:197], v[40:43]
	v_mfma_f32_16x16x32_bf16 v[28:31], v[154:157], v[202:205], v[28:31]
	v_mfma_f32_16x16x32_bf16 v[24:27], v[162:165], v[202:205], v[24:27]
	v_mfma_f32_16x16x32_bf16 v[12:15], v[154:157], v[212:215], v[12:15]
	v_mfma_f32_16x16x32_bf16 v[8:11], v[162:165], v[212:215], v[8:11]
	v_mfma_f32_16x16x32_bf16 v[52:55], v[166:169], v[182:185], v[52:55]
	v_mfma_f32_16x16x32_bf16 v[48:51], v[174:177], v[182:185], v[48:51]
	v_mfma_f32_16x16x32_bf16 v[36:39], v[166:169], v[190:193], v[36:39]
	v_mfma_f32_16x16x32_bf16 v[32:35], v[174:177], v[190:193], v[32:35]
	v_mfma_f32_16x16x32_bf16 v[20:23], v[166:169], v[198:201], v[20:23]
	v_mfma_f32_16x16x32_bf16 v[16:19], v[174:177], v[198:201], v[16:19]
	v_mfma_f32_16x16x32_bf16 v[4:7], v[166:169], v[206:209], v[4:7]
	v_mfma_f32_16x16x32_bf16 v[0:3], v[174:177], v[206:209], v[0:3]
	v_mfma_f32_16x16x32_bf16 v[52:55], v[170:173], v[186:189], v[52:55]
	v_mfma_f32_16x16x32_bf16 v[48:51], v[178:181], v[186:189], v[48:51]
	v_mfma_f32_16x16x32_bf16 v[36:39], v[170:173], v[194:197], v[36:39]
	v_mfma_f32_16x16x32_bf16 v[32:35], v[178:181], v[194:197], v[32:35]
	v_mfma_f32_16x16x32_bf16 v[20:23], v[170:173], v[202:205], v[20:23]
	v_mfma_f32_16x16x32_bf16 v[16:19], v[178:181], v[202:205], v[16:19]
	v_mfma_f32_16x16x32_bf16 v[4:7], v[170:173], v[212:215], v[4:7]
	v_mfma_f32_16x16x32_bf16 v[0:3], v[178:181], v[212:215], v[0:3]
	s_setprio 0
	s_barrier
	s_andn2_b64 vcc, exec, s[36:37]
	s_mov_b64 s[38:39], -1
	s_mov_b64 s[36:37], 0
	s_mov_b64 s[40:41], 0x100
	s_cbranch_vccz .LBB0_894
	s_and_b64 vcc, exec, s[6:7]
	s_cbranch_vccz .LBB0_897
	s_barrier

.LBB0_1155:
	v_add_u32_e32 v1, s46, v193
	ds_read_b128 v[72:75], v1
	ds_read_b128 v[76:79], v1 offset:1024
	ds_read_b128 v[84:87], v1 offset:2048
	ds_read_b128 v[188:191], v1 offset:3072
	v_add_u32_e32 v1, s47, v193
	s_add_u32 s34, s28, s30
	ds_read_b128 v[198:201], v1
	ds_read_b128 v[202:205], v1 offset:1024
	ds_read_b128 v[206:209], v1 offset:2048
	ds_read_b128 v[210:213], v1 offset:3072
	s_addc_u32 s35, s29, s31
	s_add_u32 s34, s34, 0x100
	s_addc_u32 s35, s35, 0
	s_add_u32 s53, s50, s30
	s_addc_u32 s54, s51, s31
	s_cmpk_eq_i32 s30, 0x700
	s_cselect_b32 s37, s21, s35
	s_cselect_b32 s36, s27, s34
	s_cselect_b32 s35, s19, s54
	s_cselect_b32 s34, s49, s53
	v_lshl_add_u64 v[2:3], v[112:113], 0, s[30:31]
	s_add_i32 m0, s38, 0xc000
	ds_read_b128 v[216:219], v197
	ds_read_b128 v[220:223], v197 offset:1024
	ds_read_b128 v[224:227], v197 offset:2048
	ds_read_b128 v[228:231], v197 offset:3072
	ds_read_b128 v[232:235], v197 offset:4096
	ds_read_b128 v[236:239], v197 offset:5120
	ds_read_b128 v[240:243], v197 offset:6144
	ds_read_b128 v[244:247], v197 offset:7168
	global_load_lds_dwordx4 v[2:3], off
	v_lshl_add_u64 v[2:3], v[114:115], 0, s[30:31]
	s_add_i32 m0, s38, 0xe000
	s_nop 0
	global_load_lds_dwordx4 v[2:3], off
	s_waitcnt vmcnt(8)
	s_waitcnt lgkmcnt(0)
	s_barrier
	s_setprio 1
	s_waitcnt lgkmcnt(0)
	v_mfma_f32_16x16x32_bf16 v[156:159], v[72:75], v[216:219], v[156:159]
	v_mfma_f32_16x16x32_bf16 v[160:163], v[84:87], v[216:219], v[160:163]
	v_mfma_f32_16x16x32_bf16 v[144:147], v[72:75], v[224:227], v[144:147]
	v_mfma_f32_16x16x32_bf16 v[140:143], v[84:87], v[224:227], v[140:143]
	v_mfma_f32_16x16x32_bf16 v[128:131], v[72:75], v[232:235], v[128:131]
	v_mfma_f32_16x16x32_bf16 v[124:127], v[84:87], v[232:235], v[124:127]
	v_mfma_f32_16x16x32_bf16 v[96:99], v[72:75], v[240:243], v[96:99]
	v_mfma_f32_16x16x32_bf16 v[92:95], v[84:87], v[240:243], v[92:95]
	v_mfma_f32_16x16x32_bf16 v[156:159], v[76:79], v[220:223], v[156:159]
	v_mfma_f32_16x16x32_bf16 v[160:163], v[188:191], v[220:223], v[160:163]
	v_mfma_f32_16x16x32_bf16 v[144:147], v[76:79], v[228:231], v[144:147]
	v_mfma_f32_16x16x32_bf16 v[140:143], v[188:191], v[228:231], v[140:143]
	v_mfma_f32_16x16x32_bf16 v[128:131], v[76:79], v[236:239], v[128:131]
	v_mfma_f32_16x16x32_bf16 v[124:127], v[188:191], v[236:239], v[124:127]
	v_mfma_f32_16x16x32_bf16 v[96:99], v[76:79], v[244:247], v[96:99]
	v_mfma_f32_16x16x32_bf16 v[92:95], v[188:191], v[244:247], v[92:95]
	v_mfma_f32_16x16x32_bf16 v[152:155], v[198:201], v[216:219], v[152:155]
	v_mfma_f32_16x16x32_bf16 v[148:151], v[206:209], v[216:219], v[148:151]
	v_mfma_f32_16x16x32_bf16 v[136:139], v[198:201], v[224:227], v[136:139]
	v_mfma_f32_16x16x32_bf16 v[132:135], v[206:209], v[224:227], v[132:135]
	v_mfma_f32_16x16x32_bf16 v[120:123], v[198:201], v[232:235], v[120:123]
	v_mfma_f32_16x16x32_bf16 v[116:119], v[206:209], v[232:235], v[116:119]
	v_mfma_f32_16x16x32_bf16 v[80:83], v[198:201], v[240:243], v[80:83]
	v_mfma_f32_16x16x32_bf16 v[68:71], v[206:209], v[240:243], v[68:71]
	v_mfma_f32_16x16x32_bf16 v[152:155], v[202:205], v[220:223], v[152:155]
	v_mfma_f32_16x16x32_bf16 v[148:151], v[210:213], v[220:223], v[148:151]
	v_mfma_f32_16x16x32_bf16 v[136:139], v[202:205], v[228:231], v[136:139]
	v_mfma_f32_16x16x32_bf16 v[132:135], v[210:213], v[228:231], v[132:135]
	v_mfma_f32_16x16x32_bf16 v[120:123], v[202:205], v[236:239], v[120:123]
	v_mfma_f32_16x16x32_bf16 v[116:119], v[210:213], v[236:239], v[116:119]
	v_mfma_f32_16x16x32_bf16 v[80:83], v[202:205], v[244:247], v[80:83]
	v_mfma_f32_16x16x32_bf16 v[68:71], v[210:213], v[244:247], v[68:71]
	s_setprio 0
	s_barrier
	s_add_i32 s53, s46, s33
	v_lshl_add_u64 v[248:249], s[34:35], 0, v[166:167]
	s_mov_b32 m0, s53
	ds_read_b128 v[216:219], v197 offset:16384
	ds_read_b128 v[220:223], v197 offset:17408
	ds_read_b128 v[224:227], v197 offset:18432
	ds_read_b128 v[228:231], v197 offset:19456
	ds_read_b128 v[232:235], v197 offset:20480
	ds_read_b128 v[236:239], v197 offset:21504
	ds_read_b128 v[240:243], v197 offset:22528
	ds_read_b128 v[244:247], v197 offset:23552
	global_load_lds_dwordx4 v[248:249], off
	s_add_i32 m0, s53, 0x2000
	s_add_u32 s54, s34, 0x40000
	v_lshl_add_u64 v[250:251], s[34:35], 0, v[170:171]
	s_addc_u32 s55, s35, 0
	s_add_i32 s53, s47, s33
	global_load_lds_dwordx4 v[250:251], off
	s_mov_b32 m0, s53
	v_lshl_add_u64 v[252:253], s[36:37], 0, v[164:165]
	global_load_lds_dwordx4 v166, s[54:55]
	s_add_i32 m0, s53, 0x2000
	v_lshl_add_u64 v[176:177], s[36:37], 0, v[168:169]
	global_load_lds_dwordx4 v170, s[54:55]
	s_mov_b32 m0, s38
	s_nop 0
	global_load_lds_dwordx4 v[252:253], off
	s_mov_b32 m0, s39
	s_nop 0
	global_load_lds_dwordx4 v[176:177], off
	s_waitcnt vmcnt(8)
	s_waitcnt lgkmcnt(0)
	s_barrier
	s_setprio 1
	s_waitcnt lgkmcnt(0)
	v_mfma_f32_16x16x32_bf16 v[64:67], v[72:75], v[216:219], v[64:67]
	v_mfma_f32_16x16x32_bf16 v[60:63], v[84:87], v[216:219], v[60:63]
	v_mfma_f32_16x16x32_bf16 v[48:51], v[72:75], v[224:227], v[48:51]
	v_mfma_f32_16x16x32_bf16 v[44:47], v[84:87], v[224:227], v[44:47]
	v_mfma_f32_16x16x32_bf16 v[32:35], v[72:75], v[232:235], v[32:35]
	v_mfma_f32_16x16x32_bf16 v[28:31], v[84:87], v[232:235], v[28:31]
	v_mfma_f32_16x16x32_bf16 v[16:19], v[72:75], v[240:243], v[16:19]
	v_mfma_f32_16x16x32_bf16 v[12:15], v[84:87], v[240:243], v[12:15]
	v_mfma_f32_16x16x32_bf16 v[64:67], v[76:79], v[220:223], v[64:67]
	v_mfma_f32_16x16x32_bf16 v[60:63], v[188:191], v[220:223], v[60:63]
	v_mfma_f32_16x16x32_bf16 v[48:51], v[76:79], v[228:231], v[48:51]
	v_mfma_f32_16x16x32_bf16 v[44:47], v[188:191], v[228:231], v[44:47]
	v_mfma_f32_16x16x32_bf16 v[32:35], v[76:79], v[236:239], v[32:35]
	v_mfma_f32_16x16x32_bf16 v[28:31], v[188:191], v[236:239], v[28:31]
	v_mfma_f32_16x16x32_bf16 v[16:19], v[76:79], v[244:247], v[16:19]
	v_mfma_f32_16x16x32_bf16 v[12:15], v[188:191], v[244:247], v[12:15]
	v_mfma_f32_16x16x32_bf16 v[56:59], v[198:201], v[216:219], v[56:59]
	v_mfma_f32_16x16x32_bf16 v[52:55], v[206:209], v[216:219], v[52:55]
	v_mfma_f32_16x16x32_bf16 v[40:43], v[198:201], v[224:227], v[40:43]
	v_mfma_f32_16x16x32_bf16 v[36:39], v[206:209], v[224:227], v[36:39]
	v_mfma_f32_16x16x32_bf16 v[24:27], v[198:201], v[232:235], v[24:27]
	v_mfma_f32_16x16x32_bf16 v[20:23], v[206:209], v[232:235], v[20:23]
	v_mfma_f32_16x16x32_bf16 v[8:11], v[198:201], v[240:243], v[8:11]
	v_mfma_f32_16x16x32_bf16 v[2:5], v[206:209], v[240:243], v[4:7]
	v_mfma_f32_16x16x32_bf16 v[56:59], v[202:205], v[220:223], v[56:59]
	v_mfma_f32_16x16x32_bf16 v[52:55], v[210:213], v[220:223], v[52:55]
	v_mfma_f32_16x16x32_bf16 v[40:43], v[202:205], v[228:231], v[40:43]
	v_mfma_f32_16x16x32_bf16 v[36:39], v[210:213], v[228:231], v[36:39]
	v_mfma_f32_16x16x32_bf16 v[24:27], v[202:205], v[236:239], v[24:27]
	v_mfma_f32_16x16x32_bf16 v[20:23], v[210:213], v[236:239], v[20:23]
	v_mfma_f32_16x16x32_bf16 v[8:11], v[202:205], v[244:247], v[8:11]
	v_mfma_f32_16x16x32_bf16 v[2:5], v[210:213], v[244:247], v[2:5]
	s_setprio 0
	s_barrier
	s_add_i32 s53, 0, 0x18000
	v_add_u32_e32 v1, s53, v193
	s_add_i32 s54, 0, 0x1c000
	ds_read_b128 v[72:75], v1
	ds_read_b128 v[76:79], v1 offset:1024
	ds_read_b128 v[84:87], v1 offset:2048
	ds_read_b128 v[188:191], v1 offset:3072
	v_add_u32_e32 v1, s54, v193
	ds_read_b128 v[198:201], v1
	ds_read_b128 v[202:205], v1 offset:1024
	ds_read_b128 v[206:209], v1 offset:2048
	ds_read_b128 v[210:213], v1 offset:3072
	s_add_u32 s36, s36, 0x40000
	s_addc_u32 s37, s37, 0
	s_mov_b32 m0, s40
	ds_read_b128 v[216:219], v197 offset:32768
	ds_read_b128 v[220:223], v197 offset:33792
	ds_read_b128 v[224:227], v197 offset:34816
	ds_read_b128 v[228:231], v197 offset:35840
	ds_read_b128 v[232:235], v197 offset:36864
	ds_read_b128 v[236:239], v197 offset:37888
	ds_read_b128 v[240:243], v197 offset:38912
	ds_read_b128 v[244:247], v197 offset:39936
	global_load_lds_dwordx4 v164, s[36:37]
	s_mov_b32 m0, s41
	s_nop 0
	global_load_lds_dwordx4 v168, s[36:37]
	s_waitcnt vmcnt(8)
	s_waitcnt lgkmcnt(0)
	s_barrier
	s_setprio 1
	s_waitcnt lgkmcnt(0)
	v_mfma_f32_16x16x32_bf16 v[156:159], v[72:75], v[216:219], v[156:159]
	v_mfma_f32_16x16x32_bf16 v[160:163], v[84:87], v[216:219], v[160:163]
	v_mfma_f32_16x16x32_bf16 v[144:147], v[72:75], v[224:227], v[144:147]
	v_mfma_f32_16x16x32_bf16 v[140:143], v[84:87], v[224:227], v[140:143]
	v_mfma_f32_16x16x32_bf16 v[128:131], v[72:75], v[232:235], v[128:131]
	v_mfma_f32_16x16x32_bf16 v[124:127], v[84:87], v[232:235], v[124:127]
	v_mfma_f32_16x16x32_bf16 v[96:99], v[72:75], v[240:243], v[96:99]
	v_mfma_f32_16x16x32_bf16 v[92:95], v[84:87], v[240:243], v[92:95]
	v_mfma_f32_16x16x32_bf16 v[156:159], v[76:79], v[220:223], v[156:159]
	v_mfma_f32_16x16x32_bf16 v[160:163], v[188:191], v[220:223], v[160:163]
	v_mfma_f32_16x16x32_bf16 v[144:147], v[76:79], v[228:231], v[144:147]
	v_mfma_f32_16x16x32_bf16 v[140:143], v[188:191], v[228:231], v[140:143]
	v_mfma_f32_16x16x32_bf16 v[128:131], v[76:79], v[236:239], v[128:131]
	v_mfma_f32_16x16x32_bf16 v[124:127], v[188:191], v[236:239], v[124:127]
	v_mfma_f32_16x16x32_bf16 v[96:99], v[76:79], v[244:247], v[96:99]
	v_mfma_f32_16x16x32_bf16 v[92:95], v[188:191], v[244:247], v[92:95]
	v_mfma_f32_16x16x32_bf16 v[152:155], v[198:201], v[216:219], v[152:155]
	v_mfma_f32_16x16x32_bf16 v[148:151], v[206:209], v[216:219], v[148:151]
	v_mfma_f32_16x16x32_bf16 v[136:139], v[198:201], v[224:227], v[136:139]
	v_mfma_f32_16x16x32_bf16 v[132:135], v[206:209], v[224:227], v[132:135]
	v_mfma_f32_16x16x32_bf16 v[120:123], v[198:201], v[232:235], v[120:123]
	v_mfma_f32_16x16x32_bf16 v[116:119], v[206:209], v[232:235], v[116:119]
	v_mfma_f32_16x16x32_bf16 v[80:83], v[198:201], v[240:243], v[80:83]
	v_mfma_f32_16x16x32_bf16 v[68:71], v[206:209], v[240:243], v[68:71]
	v_mfma_f32_16x16x32_bf16 v[152:155], v[202:205], v[220:223], v[152:155]
	v_mfma_f32_16x16x32_bf16 v[148:151], v[210:213], v[220:223], v[148:151]
	v_mfma_f32_16x16x32_bf16 v[136:139], v[202:205], v[228:231], v[136:139]
	v_mfma_f32_16x16x32_bf16 v[132:135], v[210:213], v[228:231], v[132:135]
	v_mfma_f32_16x16x32_bf16 v[120:123], v[202:205], v[236:239], v[120:123]
	v_mfma_f32_16x16x32_bf16 v[116:119], v[210:213], v[236:239], v[116:119]
	v_mfma_f32_16x16x32_bf16 v[80:83], v[202:205], v[244:247], v[80:83]
	v_mfma_f32_16x16x32_bf16 v[68:71], v[210:213], v[244:247], v[68:71]
	s_setprio 0
	s_barrier
	s_add_i32 s36, s53, s33
	v_lshl_add_u64 v[6:7], v[248:249], 0, s[10:11]
	s_mov_b32 m0, s36
	ds_read_b128 v[216:219], v197 offset:49152
	ds_read_b128 v[220:223], v197 offset:50176
	ds_read_b128 v[224:227], v197 offset:51200
	ds_read_b128 v[228:231], v197 offset:52224
	ds_read_b128 v[232:235], v197 offset:53248
	ds_read_b128 v[236:239], v197 offset:54272
	ds_read_b128 v[240:243], v197 offset:55296
	ds_read_b128 v[244:247], v197 offset:56320
	global_load_lds_dwordx4 v[6:7], off
	s_add_i32 m0, s36, 0x2000
	s_add_u32 s34, s34, 0x40080
	v_lshl_add_u64 v[6:7], v[250:251], 0, s[10:11]
	s_addc_u32 s35, s35, 0
	s_add_i32 s36, s54, s33
	global_load_lds_dwordx4 v[6:7], off
	s_mov_b32 m0, s36
	s_nop 0
	global_load_lds_dwordx4 v166, s[34:35]
	s_add_i32 m0, s36, 0x2000
	s_nop 0
	global_load_lds_dwordx4 v170, s[34:35]
	v_lshl_add_u64 v[6:7], v[252:253], 0, s[10:11]
	s_mov_b32 m0, s43
	s_nop 0
	global_load_lds_dwordx4 v[6:7], off
	v_lshl_add_u64 v[6:7], v[176:177], 0, s[10:11]
	s_mov_b32 m0, s44
	s_nop 0
	global_load_lds_dwordx4 v[6:7], off
	s_waitcnt vmcnt(8)
	s_waitcnt lgkmcnt(0)
	s_barrier
	s_setprio 1
	s_waitcnt lgkmcnt(0)
	v_mfma_f32_16x16x32_bf16 v[64:67], v[72:75], v[216:219], v[64:67]
	v_mfma_f32_16x16x32_bf16 v[60:63], v[84:87], v[216:219], v[60:63]
	v_mfma_f32_16x16x32_bf16 v[48:51], v[72:75], v[224:227], v[48:51]
	v_mfma_f32_16x16x32_bf16 v[44:47], v[84:87], v[224:227], v[44:47]
	v_mfma_f32_16x16x32_bf16 v[32:35], v[72:75], v[232:235], v[32:35]
	v_mfma_f32_16x16x32_bf16 v[28:31], v[84:87], v[232:235], v[28:31]
	v_mfma_f32_16x16x32_bf16 v[16:19], v[72:75], v[240:243], v[16:19]
	v_mfma_f32_16x16x32_bf16 v[12:15], v[84:87], v[240:243], v[12:15]
	v_mfma_f32_16x16x32_bf16 v[64:67], v[76:79], v[220:223], v[64:67]
	v_mfma_f32_16x16x32_bf16 v[60:63], v[188:191], v[220:223], v[60:63]
	v_mfma_f32_16x16x32_bf16 v[48:51], v[76:79], v[228:231], v[48:51]
	v_mfma_f32_16x16x32_bf16 v[44:47], v[188:191], v[228:231], v[44:47]
	v_mfma_f32_16x16x32_bf16 v[32:35], v[76:79], v[236:239], v[32:35]
	v_mfma_f32_16x16x32_bf16 v[28:31], v[188:191], v[236:239], v[28:31]
	v_mfma_f32_16x16x32_bf16 v[16:19], v[76:79], v[244:247], v[16:19]
	v_mfma_f32_16x16x32_bf16 v[12:15], v[188:191], v[244:247], v[12:15]
	v_mfma_f32_16x16x32_bf16 v[56:59], v[198:201], v[216:219], v[56:59]
	v_mfma_f32_16x16x32_bf16 v[52:55], v[206:209], v[216:219], v[52:55]
	v_mfma_f32_16x16x32_bf16 v[40:43], v[198:201], v[224:227], v[40:43]
	v_mfma_f32_16x16x32_bf16 v[36:39], v[206:209], v[224:227], v[36:39]
	v_mfma_f32_16x16x32_bf16 v[24:27], v[198:201], v[232:235], v[24:27]
	v_mfma_f32_16x16x32_bf16 v[20:23], v[206:209], v[232:235], v[20:23]
	v_mfma_f32_16x16x32_bf16 v[6:9], v[198:201], v[240:243], v[8:11]
	v_mfma_f32_16x16x32_bf16 v[2:5], v[206:209], v[240:243], v[2:5]
	v_mfma_f32_16x16x32_bf16 v[56:59], v[202:205], v[220:223], v[56:59]
	v_mfma_f32_16x16x32_bf16 v[52:55], v[210:213], v[220:223], v[52:55]
	v_mfma_f32_16x16x32_bf16 v[40:43], v[202:205], v[228:231], v[40:43]
	v_mfma_f32_16x16x32_bf16 v[36:39], v[210:213], v[228:231], v[36:39]
	v_mfma_f32_16x16x32_bf16 v[24:27], v[202:205], v[236:239], v[24:27]
	v_mfma_f32_16x16x32_bf16 v[20:23], v[210:213], v[236:239], v[20:23]
	v_mfma_f32_16x16x32_bf16 v[8:11], v[202:205], v[244:247], v[6:9]
	v_mfma_f32_16x16x32_bf16 v[4:7], v[210:213], v[244:247], v[2:5]
	s_setprio 0
	s_barrier
	s_add_i32 s52, s52, 2
	s_add_u32 s30, s30, 0x100
	s_addc_u32 s31, s31, 0
	s_cmp_gt_u32 s52, 13
	s_cbranch_scc1 .LBB0_1158

.LBB0_1243:
	ds_read_b128 v[128:131], v183
	ds_read_b128 v[132:135], v183 offset:1024
	ds_read_b128 v[136:139], v183 offset:2048
	ds_read_b128 v[140:143], v183 offset:3072
	ds_read_b128 v[144:147], v184
	ds_read_b128 v[164:167], v184 offset:1024
	ds_read_b128 v[168:171], v184 offset:2048
	ds_read_b128 v[172:175], v184 offset:3072
	s_add_u32 s20, s18, 0xfffc0080
	s_addc_u32 s21, s19, -1
	s_cmp_eq_u32 s44, 12
	s_cselect_b32 s23, s13, s21
	s_cselect_b32 s22, s40, s20
	s_cselect_b32 s21, s11, s43
	s_cselect_b32 s20, s41, s42
	s_add_i32 m0, s25, 0xc000
	ds_read_b128 v[176:179], v185
	ds_read_b128 v[188:191], v185 offset:1024
	ds_read_b128 v[192:195], v185 offset:2048
	ds_read_b128 v[196:199], v185 offset:3072
	ds_read_b128 v[200:203], v185 offset:4096
	ds_read_b128 v[204:207], v185 offset:5120
	ds_read_b128 v[208:211], v185 offset:6144
	ds_read_b128 v[216:219], v185 offset:7168
	global_load_lds_dwordx4 v156, s[18:19]
	s_add_i32 m0, s25, 0xe000
	s_nop 0
	global_load_lds_dwordx4 v158, s[18:19]
	s_waitcnt vmcnt(8)
	s_waitcnt lgkmcnt(0)
	s_barrier
	s_setprio 1
	s_waitcnt lgkmcnt(0)
	v_mfma_f32_16x16x32_bf16 v[124:127], v[128:131], v[176:179], v[124:127]
	v_mfma_f32_16x16x32_bf16 v[120:123], v[136:139], v[176:179], v[120:123]
	v_mfma_f32_16x16x32_bf16 v[116:119], v[128:131], v[192:195], v[116:119]
	v_mfma_f32_16x16x32_bf16 v[112:115], v[136:139], v[192:195], v[112:115]
	v_mfma_f32_16x16x32_bf16 v[108:111], v[128:131], v[200:203], v[108:111]
	v_mfma_f32_16x16x32_bf16 v[100:103], v[136:139], v[200:203], v[100:103]
	v_mfma_f32_16x16x32_bf16 v[88:91], v[128:131], v[208:211], v[88:91]
	v_mfma_f32_16x16x32_bf16 v[80:83], v[136:139], v[208:211], v[80:83]
	v_mfma_f32_16x16x32_bf16 v[124:127], v[132:135], v[188:191], v[124:127]
	v_mfma_f32_16x16x32_bf16 v[120:123], v[140:143], v[188:191], v[120:123]
	v_mfma_f32_16x16x32_bf16 v[116:119], v[132:135], v[196:199], v[116:119]
	v_mfma_f32_16x16x32_bf16 v[112:115], v[140:143], v[196:199], v[112:115]
	v_mfma_f32_16x16x32_bf16 v[108:111], v[132:135], v[204:207], v[108:111]
	v_mfma_f32_16x16x32_bf16 v[100:103], v[140:143], v[204:207], v[100:103]
	v_mfma_f32_16x16x32_bf16 v[88:91], v[132:135], v[216:219], v[88:91]
	v_mfma_f32_16x16x32_bf16 v[80:83], v[140:143], v[216:219], v[80:83]
	v_mfma_f32_16x16x32_bf16 v[104:107], v[144:147], v[176:179], v[104:107]
	v_mfma_f32_16x16x32_bf16 v[96:99], v[168:171], v[176:179], v[96:99]
	v_mfma_f32_16x16x32_bf16 v[92:95], v[144:147], v[192:195], v[92:95]
	v_mfma_f32_16x16x32_bf16 v[84:87], v[168:171], v[192:195], v[84:87]
	v_mfma_f32_16x16x32_bf16 v[76:79], v[144:147], v[200:203], v[76:79]
	v_mfma_f32_16x16x32_bf16 v[72:75], v[168:171], v[200:203], v[72:75]
	v_mfma_f32_16x16x32_bf16 v[68:71], v[144:147], v[208:211], v[68:71]
	v_mfma_f32_16x16x32_bf16 v[64:67], v[168:171], v[208:211], v[64:67]
	v_mfma_f32_16x16x32_bf16 v[104:107], v[164:167], v[188:191], v[104:107]
	v_mfma_f32_16x16x32_bf16 v[96:99], v[172:175], v[188:191], v[96:99]
	v_mfma_f32_16x16x32_bf16 v[92:95], v[164:167], v[196:199], v[92:95]
	v_mfma_f32_16x16x32_bf16 v[84:87], v[172:175], v[196:199], v[84:87]
	v_mfma_f32_16x16x32_bf16 v[76:79], v[164:167], v[204:207], v[76:79]
	v_mfma_f32_16x16x32_bf16 v[72:75], v[172:175], v[204:207], v[72:75]
	v_mfma_f32_16x16x32_bf16 v[68:71], v[164:167], v[216:219], v[68:71]
	v_mfma_f32_16x16x32_bf16 v[64:67], v[172:175], v[216:219], v[64:67]
	s_setprio 0
	s_barrier
	s_add_i32 s45, s36, s24
	v_lshl_add_u64 v[212:213], s[20:21], 0, v[152:153]
	s_mov_b32 m0, s45
	ds_read_b128 v[176:179], v185 offset:16384
	ds_read_b128 v[188:191], v185 offset:17408
	ds_read_b128 v[192:195], v185 offset:18432
	ds_read_b128 v[196:199], v185 offset:19456
	ds_read_b128 v[200:203], v185 offset:20480
	ds_read_b128 v[204:207], v185 offset:21504
	ds_read_b128 v[208:211], v185 offset:22528
	ds_read_b128 v[216:219], v185 offset:23552
	global_load_lds_dwordx4 v[212:213], off
	s_add_i32 m0, s45, 0x2000
	s_add_u32 s46, s20, 0x40000
	v_lshl_add_u64 v[220:221], s[20:21], 0, v[148:149]
	s_addc_u32 s47, s21, 0
	s_add_i32 s45, s37, s24
	global_load_lds_dwordx4 v[220:221], off
	s_mov_b32 m0, s45
	v_lshl_add_u64 v[224:225], s[22:23], 0, v[150:151]
	global_load_lds_dwordx4 v152, s[46:47]
	s_add_i32 m0, s45, 0x2000
	s_nop 0
	global_load_lds_dwordx4 v148, s[46:47]
	v_lshl_add_u64 v[222:223], s[22:23], 0, v[154:155]
	s_mov_b32 m0, s25
	s_nop 0
	global_load_lds_dwordx4 v[222:223], off
	s_mov_b32 m0, s26
	s_nop 0
	global_load_lds_dwordx4 v[224:225], off
	s_waitcnt vmcnt(8)
	s_waitcnt lgkmcnt(0)
	s_barrier
	s_setprio 1
	s_waitcnt lgkmcnt(0)
	v_mfma_f32_16x16x32_bf16 v[60:63], v[128:131], v[176:179], v[60:63]
	v_mfma_f32_16x16x32_bf16 v[56:59], v[136:139], v[176:179], v[56:59]
	v_mfma_f32_16x16x32_bf16 v[52:55], v[128:131], v[192:195], v[52:55]
	v_mfma_f32_16x16x32_bf16 v[48:51], v[136:139], v[192:195], v[48:51]
	v_mfma_f32_16x16x32_bf16 v[40:43], v[128:131], v[200:203], v[40:43]
	v_mfma_f32_16x16x32_bf16 v[32:35], v[136:139], v[200:203], v[32:35]
	v_mfma_f32_16x16x32_bf16 v[20:23], v[128:131], v[208:211], v[20:23]
	v_mfma_f32_16x16x32_bf16 v[16:19], v[136:139], v[208:211], v[16:19]
	v_mfma_f32_16x16x32_bf16 v[60:63], v[132:135], v[188:191], v[60:63]
	v_mfma_f32_16x16x32_bf16 v[56:59], v[140:143], v[188:191], v[56:59]
	v_mfma_f32_16x16x32_bf16 v[52:55], v[132:135], v[196:199], v[52:55]
	v_mfma_f32_16x16x32_bf16 v[48:51], v[140:143], v[196:199], v[48:51]
	v_mfma_f32_16x16x32_bf16 v[40:43], v[132:135], v[204:207], v[40:43]
	v_mfma_f32_16x16x32_bf16 v[32:35], v[140:143], v[204:207], v[32:35]
	v_mfma_f32_16x16x32_bf16 v[20:23], v[132:135], v[216:219], v[20:23]
	v_mfma_f32_16x16x32_bf16 v[16:19], v[140:143], v[216:219], v[16:19]
	v_mfma_f32_16x16x32_bf16 v[44:47], v[144:147], v[176:179], v[44:47]
	v_mfma_f32_16x16x32_bf16 v[36:39], v[168:171], v[176:179], v[36:39]
	v_mfma_f32_16x16x32_bf16 v[28:31], v[144:147], v[192:195], v[28:31]
	v_mfma_f32_16x16x32_bf16 v[24:27], v[168:171], v[192:195], v[24:27]
	v_mfma_f32_16x16x32_bf16 v[12:15], v[144:147], v[200:203], v[12:15]
	v_mfma_f32_16x16x32_bf16 v[8:11], v[168:171], v[200:203], v[8:11]
	v_mfma_f32_16x16x32_bf16 v[4:7], v[144:147], v[208:211], v[4:7]
	v_mfma_f32_16x16x32_bf16 v[0:3], v[168:171], v[208:211], v[0:3]
	v_mfma_f32_16x16x32_bf16 v[44:47], v[164:167], v[188:191], v[44:47]
	v_mfma_f32_16x16x32_bf16 v[36:39], v[172:175], v[188:191], v[36:39]
	v_mfma_f32_16x16x32_bf16 v[28:31], v[164:167], v[196:199], v[28:31]
	v_mfma_f32_16x16x32_bf16 v[24:27], v[172:175], v[196:199], v[24:27]
	v_mfma_f32_16x16x32_bf16 v[12:15], v[164:167], v[204:207], v[12:15]
	v_mfma_f32_16x16x32_bf16 v[8:11], v[172:175], v[204:207], v[8:11]
	v_mfma_f32_16x16x32_bf16 v[4:7], v[164:167], v[216:219], v[4:7]
	v_mfma_f32_16x16x32_bf16 v[0:3], v[172:175], v[216:219], v[0:3]
	s_setprio 0
	s_barrier
	s_add_i32 s45, 0, 0x18000
	s_add_i32 s46, 0, 0x1c000
	v_add_u32_e32 v140, s45, v181
	v_add_u32_e32 v172, s46, v181
	ds_read_b128 v[128:131], v140
	ds_read_b128 v[132:135], v140 offset:1024
	ds_read_b128 v[136:139], v140 offset:2048
	ds_read_b128 v[140:143], v140 offset:3072
	ds_read_b128 v[144:147], v172
	ds_read_b128 v[164:167], v172 offset:1024
	ds_read_b128 v[168:171], v172 offset:2048
	ds_read_b128 v[172:175], v172 offset:3072
	s_add_u32 s22, s22, 0x40000
	s_addc_u32 s23, s23, 0
	s_mov_b32 m0, s27
	ds_read_b128 v[176:179], v185 offset:32768
	ds_read_b128 v[188:191], v185 offset:33792
	ds_read_b128 v[192:195], v185 offset:34816
	ds_read_b128 v[196:199], v185 offset:35840
	ds_read_b128 v[200:203], v185 offset:36864
	ds_read_b128 v[204:207], v185 offset:37888
	ds_read_b128 v[208:211], v185 offset:38912
	ds_read_b128 v[216:219], v185 offset:39936
	global_load_lds_dwordx4 v154, s[22:23]
	s_mov_b32 m0, s28
	s_nop 0
	global_load_lds_dwordx4 v150, s[22:23]
	s_waitcnt vmcnt(8)
	s_waitcnt lgkmcnt(0)
	s_barrier
	s_setprio 1
	s_waitcnt lgkmcnt(0)
	v_mfma_f32_16x16x32_bf16 v[124:127], v[128:131], v[176:179], v[124:127]
	v_mfma_f32_16x16x32_bf16 v[120:123], v[136:139], v[176:179], v[120:123]
	v_mfma_f32_16x16x32_bf16 v[116:119], v[128:131], v[192:195], v[116:119]
	v_mfma_f32_16x16x32_bf16 v[112:115], v[136:139], v[192:195], v[112:115]
	v_mfma_f32_16x16x32_bf16 v[108:111], v[128:131], v[200:203], v[108:111]
	v_mfma_f32_16x16x32_bf16 v[100:103], v[136:139], v[200:203], v[100:103]
	v_mfma_f32_16x16x32_bf16 v[88:91], v[128:131], v[208:211], v[88:91]
	v_mfma_f32_16x16x32_bf16 v[80:83], v[136:139], v[208:211], v[80:83]
	v_mfma_f32_16x16x32_bf16 v[124:127], v[132:135], v[188:191], v[124:127]
	v_mfma_f32_16x16x32_bf16 v[120:123], v[140:143], v[188:191], v[120:123]
	v_mfma_f32_16x16x32_bf16 v[116:119], v[132:135], v[196:199], v[116:119]
	v_mfma_f32_16x16x32_bf16 v[112:115], v[140:143], v[196:199], v[112:115]
	v_mfma_f32_16x16x32_bf16 v[108:111], v[132:135], v[204:207], v[108:111]
	v_mfma_f32_16x16x32_bf16 v[100:103], v[140:143], v[204:207], v[100:103]
	v_mfma_f32_16x16x32_bf16 v[88:91], v[132:135], v[216:219], v[88:91]
	v_mfma_f32_16x16x32_bf16 v[80:83], v[140:143], v[216:219], v[80:83]
	v_mfma_f32_16x16x32_bf16 v[104:107], v[144:147], v[176:179], v[104:107]
	v_mfma_f32_16x16x32_bf16 v[96:99], v[168:171], v[176:179], v[96:99]
	v_mfma_f32_16x16x32_bf16 v[92:95], v[144:147], v[192:195], v[92:95]
	v_mfma_f32_16x16x32_bf16 v[84:87], v[168:171], v[192:195], v[84:87]
	v_mfma_f32_16x16x32_bf16 v[76:79], v[144:147], v[200:203], v[76:79]
	v_mfma_f32_16x16x32_bf16 v[72:75], v[168:171], v[200:203], v[72:75]
	v_mfma_f32_16x16x32_bf16 v[68:71], v[144:147], v[208:211], v[68:71]
	v_mfma_f32_16x16x32_bf16 v[64:67], v[168:171], v[208:211], v[64:67]
	v_mfma_f32_16x16x32_bf16 v[104:107], v[164:167], v[188:191], v[104:107]
	v_mfma_f32_16x16x32_bf16 v[96:99], v[172:175], v[188:191], v[96:99]
	v_mfma_f32_16x16x32_bf16 v[92:95], v[164:167], v[196:199], v[92:95]
	v_mfma_f32_16x16x32_bf16 v[84:87], v[172:175], v[196:199], v[84:87]
	v_mfma_f32_16x16x32_bf16 v[76:79], v[164:167], v[204:207], v[76:79]
	v_mfma_f32_16x16x32_bf16 v[72:75], v[172:175], v[204:207], v[72:75]
	v_mfma_f32_16x16x32_bf16 v[68:71], v[164:167], v[216:219], v[68:71]
	v_mfma_f32_16x16x32_bf16 v[64:67], v[172:175], v[216:219], v[64:67]
	s_setprio 0
	s_barrier
	s_add_i32 s22, s45, s24
	v_lshl_add_u64 v[212:213], v[212:213], 0, s[6:7]
	s_mov_b32 m0, s22
	ds_read_b128 v[176:179], v185 offset:49152
	ds_read_b128 v[188:191], v185 offset:50176
	ds_read_b128 v[192:195], v185 offset:51200
	ds_read_b128 v[196:199], v185 offset:52224
	ds_read_b128 v[200:203], v185 offset:53248
	ds_read_b128 v[204:207], v185 offset:54272
	ds_read_b128 v[208:211], v185 offset:55296
	ds_read_b128 v[216:219], v185 offset:56320
	global_load_lds_dwordx4 v[212:213], off
	s_add_i32 m0, s22, 0x2000
	s_add_u32 s20, s20, 0x40080
	v_lshl_add_u64 v[212:213], v[220:221], 0, s[6:7]
	s_addc_u32 s21, s21, 0
	s_add_i32 s22, s46, s24
	global_load_lds_dwordx4 v[212:213], off
	s_mov_b32 m0, s22
	s_nop 0
	global_load_lds_dwordx4 v152, s[20:21]
	s_add_i32 m0, s22, 0x2000
	s_nop 0
	global_load_lds_dwordx4 v148, s[20:21]
	v_lshl_add_u64 v[212:213], v[222:223], 0, s[6:7]
	s_mov_b32 m0, s33
	s_nop 0
	global_load_lds_dwordx4 v[212:213], off
	v_lshl_add_u64 v[212:213], v[224:225], 0, s[6:7]
	s_mov_b32 m0, s34
	s_nop 0
	global_load_lds_dwordx4 v[212:213], off
	s_waitcnt vmcnt(8)
	s_waitcnt lgkmcnt(0)
	s_barrier
	s_setprio 1
	s_waitcnt lgkmcnt(0)
	v_mfma_f32_16x16x32_bf16 v[60:63], v[128:131], v[176:179], v[60:63]
	v_mfma_f32_16x16x32_bf16 v[56:59], v[136:139], v[176:179], v[56:59]
	v_mfma_f32_16x16x32_bf16 v[52:55], v[128:131], v[192:195], v[52:55]
	v_mfma_f32_16x16x32_bf16 v[48:51], v[136:139], v[192:195], v[48:51]
	v_mfma_f32_16x16x32_bf16 v[40:43], v[128:131], v[200:203], v[40:43]
	v_mfma_f32_16x16x32_bf16 v[32:35], v[136:139], v[200:203], v[32:35]
	v_mfma_f32_16x16x32_bf16 v[20:23], v[128:131], v[208:211], v[20:23]
	v_mfma_f32_16x16x32_bf16 v[16:19], v[136:139], v[208:211], v[16:19]
	v_mfma_f32_16x16x32_bf16 v[60:63], v[132:135], v[188:191], v[60:63]
	v_mfma_f32_16x16x32_bf16 v[56:59], v[140:143], v[188:191], v[56:59]
	v_mfma_f32_16x16x32_bf16 v[52:55], v[132:135], v[196:199], v[52:55]
	v_mfma_f32_16x16x32_bf16 v[48:51], v[140:143], v[196:199], v[48:51]
	v_mfma_f32_16x16x32_bf16 v[40:43], v[132:135], v[204:207], v[40:43]
	v_mfma_f32_16x16x32_bf16 v[32:35], v[140:143], v[204:207], v[32:35]
	v_mfma_f32_16x16x32_bf16 v[20:23], v[132:135], v[216:219], v[20:23]
	v_mfma_f32_16x16x32_bf16 v[16:19], v[140:143], v[216:219], v[16:19]
	v_mfma_f32_16x16x32_bf16 v[44:47], v[144:147], v[176:179], v[44:47]
	v_mfma_f32_16x16x32_bf16 v[36:39], v[168:171], v[176:179], v[36:39]
	v_mfma_f32_16x16x32_bf16 v[28:31], v[144:147], v[192:195], v[28:31]
	v_mfma_f32_16x16x32_bf16 v[24:27], v[168:171], v[192:195], v[24:27]
	v_mfma_f32_16x16x32_bf16 v[12:15], v[144:147], v[200:203], v[12:15]
	v_mfma_f32_16x16x32_bf16 v[8:11], v[168:171], v[200:203], v[8:11]
	v_mfma_f32_16x16x32_bf16 v[4:7], v[144:147], v[208:211], v[4:7]
	v_mfma_f32_16x16x32_bf16 v[0:3], v[168:171], v[208:211], v[0:3]
	v_mfma_f32_16x16x32_bf16 v[44:47], v[164:167], v[188:191], v[44:47]
	v_mfma_f32_16x16x32_bf16 v[36:39], v[172:175], v[188:191], v[36:39]
	v_mfma_f32_16x16x32_bf16 v[28:31], v[164:167], v[196:199], v[28:31]
	v_mfma_f32_16x16x32_bf16 v[24:27], v[172:175], v[196:199], v[24:27]
	v_mfma_f32_16x16x32_bf16 v[12:15], v[164:167], v[204:207], v[12:15]
	v_mfma_f32_16x16x32_bf16 v[8:11], v[172:175], v[204:207], v[8:11]
	v_mfma_f32_16x16x32_bf16 v[4:7], v[164:167], v[216:219], v[4:7]
	v_mfma_f32_16x16x32_bf16 v[0:3], v[172:175], v[216:219], v[0:3]
	s_setprio 0
	s_barrier
	s_add_i32 s44, s44, 2
	s_add_u32 s18, s18, 0x100
	s_addc_u32 s19, s19, 0
	s_add_u32 s42, s42, 0x100
	s_addc_u32 s43, s43, 0
	s_cmp_gt_u32 s44, 13
	s_cbranch_scc0 .LBB0_1243
	s_and_b64 vcc, exec, s[8:9]
	s_cbranch_vccz .LBB0_1246
	s_barrier

.LBB0_1325:
	ds_read_b128 v[120:123], v209
	ds_read_b128 v[128:131], v209 offset:1024
	ds_read_b128 v[136:139], v209 offset:2048
	ds_read_b128 v[140:143], v209 offset:3072
	ds_read_b128 v[144:147], v210
	ds_read_b128 v[148:151], v210 offset:1024
	ds_read_b128 v[152:155], v210 offset:2048
	ds_read_b128 v[156:159], v210 offset:3072
	s_add_u32 s4, s22, 0x100
	s_addc_u32 s5, s23, 0
	s_cmp_eq_u32 s47, 40
	s_cselect_b32 s27, s17, s5
	s_cselect_b32 s26, s16, s4
	s_cselect_b32 s25, s19, s46
	s_cselect_b32 s24, s18, s21
	s_add_i32 m0, s29, 0xc000
	ds_read_b128 v[160:163], v211
	ds_read_b128 v[164:167], v211 offset:1024
	ds_read_b128 v[184:187], v211 offset:2048
	ds_read_b128 v[188:191], v211 offset:3072
	ds_read_b128 v[192:195], v211 offset:4096
	ds_read_b128 v[196:199], v211 offset:5120
	ds_read_b128 v[200:203], v211 offset:6144
	ds_read_b128 v[216:219], v211 offset:7168
	global_load_lds_dwordx4 v176, s[22:23]
	s_add_i32 m0, s29, 0xe000
	s_nop 0
	global_load_lds_dwordx4 v178, s[22:23]
	s_waitcnt vmcnt(8)
	s_waitcnt lgkmcnt(0)
	s_barrier
	s_setprio 1
	s_waitcnt lgkmcnt(0)
	v_mfma_f32_16x16x32_bf16 v[132:135], v[120:123], v[160:163], v[132:135]
	v_mfma_f32_16x16x32_bf16 v[124:127], v[136:139], v[160:163], v[124:127]
	v_mfma_f32_16x16x32_bf16 v[108:111], v[120:123], v[184:187], v[108:111]
	v_mfma_f32_16x16x32_bf16 v[104:107], v[136:139], v[184:187], v[104:107]
	v_mfma_f32_16x16x32_bf16 v[92:95], v[120:123], v[192:195], v[92:95]
	v_mfma_f32_16x16x32_bf16 v[88:91], v[136:139], v[192:195], v[88:91]
	v_mfma_f32_16x16x32_bf16 v[76:79], v[120:123], v[200:203], v[76:79]
	v_mfma_f32_16x16x32_bf16 v[72:75], v[136:139], v[200:203], v[72:75]
	v_mfma_f32_16x16x32_bf16 v[132:135], v[128:131], v[164:167], v[132:135]
	v_mfma_f32_16x16x32_bf16 v[124:127], v[140:143], v[164:167], v[124:127]
	v_mfma_f32_16x16x32_bf16 v[108:111], v[128:131], v[188:191], v[108:111]
	v_mfma_f32_16x16x32_bf16 v[104:107], v[140:143], v[188:191], v[104:107]
	v_mfma_f32_16x16x32_bf16 v[92:95], v[128:131], v[196:199], v[92:95]
	v_mfma_f32_16x16x32_bf16 v[88:91], v[140:143], v[196:199], v[88:91]
	v_mfma_f32_16x16x32_bf16 v[76:79], v[128:131], v[216:219], v[76:79]
	v_mfma_f32_16x16x32_bf16 v[72:75], v[140:143], v[216:219], v[72:75]
	v_mfma_f32_16x16x32_bf16 v[116:119], v[144:147], v[160:163], v[116:119]
	v_mfma_f32_16x16x32_bf16 v[112:115], v[152:155], v[160:163], v[112:115]
	v_mfma_f32_16x16x32_bf16 v[100:103], v[144:147], v[184:187], v[100:103]
	v_mfma_f32_16x16x32_bf16 v[96:99], v[152:155], v[184:187], v[96:99]
	v_mfma_f32_16x16x32_bf16 v[84:87], v[144:147], v[192:195], v[84:87]
	v_mfma_f32_16x16x32_bf16 v[80:83], v[152:155], v[192:195], v[80:83]
	v_mfma_f32_16x16x32_bf16 v[68:71], v[144:147], v[200:203], v[68:71]
	v_mfma_f32_16x16x32_bf16 v[64:67], v[152:155], v[200:203], v[64:67]
	v_mfma_f32_16x16x32_bf16 v[116:119], v[148:151], v[164:167], v[116:119]
	v_mfma_f32_16x16x32_bf16 v[112:115], v[156:159], v[164:167], v[112:115]
	v_mfma_f32_16x16x32_bf16 v[100:103], v[148:151], v[188:191], v[100:103]
	v_mfma_f32_16x16x32_bf16 v[96:99], v[156:159], v[188:191], v[96:99]
	v_mfma_f32_16x16x32_bf16 v[84:87], v[148:151], v[196:199], v[84:87]
	v_mfma_f32_16x16x32_bf16 v[80:83], v[156:159], v[196:199], v[80:83]
	v_mfma_f32_16x16x32_bf16 v[68:71], v[148:151], v[216:219], v[68:71]
	v_mfma_f32_16x16x32_bf16 v[64:67], v[156:159], v[216:219], v[64:67]
	s_setprio 0
	s_barrier
	s_add_i32 s22, s41, s28
	v_lshl_add_u64 v[220:221], s[24:25], 0, v[170:171]
	s_mov_b32 m0, s22
	ds_read_b128 v[160:163], v211 offset:16384
	ds_read_b128 v[164:167], v211 offset:17408
	ds_read_b128 v[184:187], v211 offset:18432
	ds_read_b128 v[188:191], v211 offset:19456
	ds_read_b128 v[192:195], v211 offset:20480
	ds_read_b128 v[196:199], v211 offset:21504
	ds_read_b128 v[200:203], v211 offset:22528
	ds_read_b128 v[216:219], v211 offset:23552
	global_load_lds_dwordx4 v[220:221], off
	s_add_i32 m0, s22, 0x2000
	s_add_u32 s22, s24, 0xb0000
	v_lshl_add_u64 v[222:223], s[24:25], 0, v[174:175]
	s_addc_u32 s23, s25, 0
	s_add_i32 s48, s42, s28
	global_load_lds_dwordx4 v[222:223], off
	s_mov_b32 m0, s48
	v_lshl_add_u64 v[226:227], s[26:27], 0, v[172:173]
	global_load_lds_dwordx4 v170, s[22:23]
	s_add_i32 m0, s48, 0x2000
	s_nop 0
	global_load_lds_dwordx4 v174, s[22:23]
	v_lshl_add_u64 v[224:225], s[26:27], 0, v[168:169]
	s_mov_b32 m0, s29
	s_nop 0
	global_load_lds_dwordx4 v[224:225], off
	s_mov_b32 m0, s30
	s_nop 0
	global_load_lds_dwordx4 v[226:227], off
	s_waitcnt vmcnt(8)
	s_waitcnt lgkmcnt(0)
	s_barrier
	s_setprio 1
	s_waitcnt lgkmcnt(0)
	v_mfma_f32_16x16x32_bf16 v[60:63], v[120:123], v[160:163], v[60:63]
	v_mfma_f32_16x16x32_bf16 v[56:59], v[136:139], v[160:163], v[56:59]
	v_mfma_f32_16x16x32_bf16 v[44:47], v[120:123], v[184:187], v[44:47]
	v_mfma_f32_16x16x32_bf16 v[40:43], v[136:139], v[184:187], v[40:43]
	v_mfma_f32_16x16x32_bf16 v[28:31], v[120:123], v[192:195], v[28:31]
	v_mfma_f32_16x16x32_bf16 v[24:27], v[136:139], v[192:195], v[24:27]
	v_mfma_f32_16x16x32_bf16 v[12:15], v[120:123], v[200:203], v[12:15]
	v_mfma_f32_16x16x32_bf16 v[8:11], v[136:139], v[200:203], v[8:11]
	v_mfma_f32_16x16x32_bf16 v[60:63], v[128:131], v[164:167], v[60:63]
	v_mfma_f32_16x16x32_bf16 v[56:59], v[140:143], v[164:167], v[56:59]
	v_mfma_f32_16x16x32_bf16 v[44:47], v[128:131], v[188:191], v[44:47]
	v_mfma_f32_16x16x32_bf16 v[40:43], v[140:143], v[188:191], v[40:43]
	v_mfma_f32_16x16x32_bf16 v[28:31], v[128:131], v[196:199], v[28:31]
	v_mfma_f32_16x16x32_bf16 v[24:27], v[140:143], v[196:199], v[24:27]
	v_mfma_f32_16x16x32_bf16 v[12:15], v[128:131], v[216:219], v[12:15]
	v_mfma_f32_16x16x32_bf16 v[8:11], v[140:143], v[216:219], v[8:11]
	v_mfma_f32_16x16x32_bf16 v[52:55], v[144:147], v[160:163], v[52:55]
	v_mfma_f32_16x16x32_bf16 v[48:51], v[152:155], v[160:163], v[48:51]
	v_mfma_f32_16x16x32_bf16 v[36:39], v[144:147], v[184:187], v[36:39]
	v_mfma_f32_16x16x32_bf16 v[32:35], v[152:155], v[184:187], v[32:35]
	v_mfma_f32_16x16x32_bf16 v[20:23], v[144:147], v[192:195], v[20:23]
	v_mfma_f32_16x16x32_bf16 v[16:19], v[152:155], v[192:195], v[16:19]
	v_mfma_f32_16x16x32_bf16 v[4:7], v[144:147], v[200:203], v[4:7]
	v_mfma_f32_16x16x32_bf16 v[0:3], v[152:155], v[200:203], v[0:3]
	v_mfma_f32_16x16x32_bf16 v[52:55], v[148:151], v[164:167], v[52:55]
	v_mfma_f32_16x16x32_bf16 v[48:51], v[156:159], v[164:167], v[48:51]
	v_mfma_f32_16x16x32_bf16 v[36:39], v[148:151], v[188:191], v[36:39]
	v_mfma_f32_16x16x32_bf16 v[32:35], v[156:159], v[188:191], v[32:35]
	v_mfma_f32_16x16x32_bf16 v[20:23], v[148:151], v[196:199], v[20:23]
	v_mfma_f32_16x16x32_bf16 v[16:19], v[156:159], v[196:199], v[16:19]
	v_mfma_f32_16x16x32_bf16 v[4:7], v[148:151], v[216:219], v[4:7]
	v_mfma_f32_16x16x32_bf16 v[0:3], v[156:159], v[216:219], v[0:3]
	s_setprio 0
	s_barrier
	s_add_i32 s48, 0, 0x18000
	s_add_i32 s49, 0, 0x1c000
	v_add_u32_e32 v140, s48, v205
	v_add_u32_e32 v156, s49, v205
	ds_read_b128 v[120:123], v140
	ds_read_b128 v[128:131], v140 offset:1024
	ds_read_b128 v[136:139], v140 offset:2048
	ds_read_b128 v[140:143], v140 offset:3072
	ds_read_b128 v[144:147], v156
	ds_read_b128 v[148:151], v156 offset:1024
	ds_read_b128 v[152:155], v156 offset:2048
	ds_read_b128 v[156:159], v156 offset:3072
	s_add_u32 s22, s26, 0xb0000
	s_addc_u32 s23, s27, 0
	s_mov_b32 m0, s31
	ds_read_b128 v[160:163], v211 offset:32768
	ds_read_b128 v[164:167], v211 offset:33792
	ds_read_b128 v[184:187], v211 offset:34816
	ds_read_b128 v[188:191], v211 offset:35840
	ds_read_b128 v[192:195], v211 offset:36864
	ds_read_b128 v[196:199], v211 offset:37888
	ds_read_b128 v[200:203], v211 offset:38912
	ds_read_b128 v[216:219], v211 offset:39936
	global_load_lds_dwordx4 v168, s[22:23]
	s_mov_b32 m0, s33
	s_nop 0
	global_load_lds_dwordx4 v172, s[22:23]
	s_waitcnt vmcnt(8)
	s_waitcnt lgkmcnt(0)
	s_barrier
	s_setprio 1
	s_waitcnt lgkmcnt(0)
	v_mfma_f32_16x16x32_bf16 v[132:135], v[120:123], v[160:163], v[132:135]
	v_mfma_f32_16x16x32_bf16 v[124:127], v[136:139], v[160:163], v[124:127]
	v_mfma_f32_16x16x32_bf16 v[108:111], v[120:123], v[184:187], v[108:111]
	v_mfma_f32_16x16x32_bf16 v[104:107], v[136:139], v[184:187], v[104:107]
	v_mfma_f32_16x16x32_bf16 v[92:95], v[120:123], v[192:195], v[92:95]
	v_mfma_f32_16x16x32_bf16 v[88:91], v[136:139], v[192:195], v[88:91]
	v_mfma_f32_16x16x32_bf16 v[76:79], v[120:123], v[200:203], v[76:79]
	v_mfma_f32_16x16x32_bf16 v[72:75], v[136:139], v[200:203], v[72:75]
	v_mfma_f32_16x16x32_bf16 v[132:135], v[128:131], v[164:167], v[132:135]
	v_mfma_f32_16x16x32_bf16 v[124:127], v[140:143], v[164:167], v[124:127]
	v_mfma_f32_16x16x32_bf16 v[108:111], v[128:131], v[188:191], v[108:111]
	v_mfma_f32_16x16x32_bf16 v[104:107], v[140:143], v[188:191], v[104:107]
	v_mfma_f32_16x16x32_bf16 v[92:95], v[128:131], v[196:199], v[92:95]
	v_mfma_f32_16x16x32_bf16 v[88:91], v[140:143], v[196:199], v[88:91]
	v_mfma_f32_16x16x32_bf16 v[76:79], v[128:131], v[216:219], v[76:79]
	v_mfma_f32_16x16x32_bf16 v[72:75], v[140:143], v[216:219], v[72:75]
	v_mfma_f32_16x16x32_bf16 v[116:119], v[144:147], v[160:163], v[116:119]
	v_mfma_f32_16x16x32_bf16 v[112:115], v[152:155], v[160:163], v[112:115]
	v_mfma_f32_16x16x32_bf16 v[100:103], v[144:147], v[184:187], v[100:103]
	v_mfma_f32_16x16x32_bf16 v[96:99], v[152:155], v[184:187], v[96:99]
	v_mfma_f32_16x16x32_bf16 v[84:87], v[144:147], v[192:195], v[84:87]
	v_mfma_f32_16x16x32_bf16 v[80:83], v[152:155], v[192:195], v[80:83]
	v_mfma_f32_16x16x32_bf16 v[68:71], v[144:147], v[200:203], v[68:71]
	v_mfma_f32_16x16x32_bf16 v[64:67], v[152:155], v[200:203], v[64:67]
	v_mfma_f32_16x16x32_bf16 v[116:119], v[148:151], v[164:167], v[116:119]
	v_mfma_f32_16x16x32_bf16 v[112:115], v[156:159], v[164:167], v[112:115]
	v_mfma_f32_16x16x32_bf16 v[100:103], v[148:151], v[188:191], v[100:103]
	v_mfma_f32_16x16x32_bf16 v[96:99], v[156:159], v[188:191], v[96:99]
	v_mfma_f32_16x16x32_bf16 v[84:87], v[148:151], v[196:199], v[84:87]
	v_mfma_f32_16x16x32_bf16 v[80:83], v[156:159], v[196:199], v[80:83]
	v_mfma_f32_16x16x32_bf16 v[68:71], v[148:151], v[216:219], v[68:71]
	v_mfma_f32_16x16x32_bf16 v[64:67], v[156:159], v[216:219], v[64:67]
	s_setprio 0
	s_barrier
	s_add_i32 s22, s48, s28
	v_lshl_add_u64 v[220:221], v[220:221], 0, s[8:9]
	s_mov_b32 m0, s22
	ds_read_b128 v[160:163], v211 offset:49152
	ds_read_b128 v[164:167], v211 offset:50176
	ds_read_b128 v[184:187], v211 offset:51200
	ds_read_b128 v[188:191], v211 offset:52224
	ds_read_b128 v[192:195], v211 offset:53248
	ds_read_b128 v[196:199], v211 offset:54272
	ds_read_b128 v[200:203], v211 offset:55296
	ds_read_b128 v[216:219], v211 offset:56320
	global_load_lds_dwordx4 v[220:221], off
	s_add_i32 m0, s22, 0x2000
	s_add_u32 s22, s24, 0xb0080
	v_lshl_add_u64 v[220:221], v[222:223], 0, s[8:9]
	s_addc_u32 s23, s25, 0
	s_add_i32 s24, s49, s28
	global_load_lds_dwordx4 v[220:221], off
	s_mov_b32 m0, s24
	s_nop 0
	global_load_lds_dwordx4 v170, s[22:23]
	s_add_i32 m0, s24, 0x2000
	s_nop 0
	global_load_lds_dwordx4 v174, s[22:23]
	v_lshl_add_u64 v[220:221], v[224:225], 0, s[8:9]
	s_mov_b32 m0, s37
	s_nop 0
	global_load_lds_dwordx4 v[220:221], off
	v_lshl_add_u64 v[220:221], v[226:227], 0, s[8:9]
	s_mov_b32 m0, s38
	s_nop 0
	global_load_lds_dwordx4 v[220:221], off
	s_waitcnt vmcnt(8)
	s_waitcnt lgkmcnt(0)
	s_barrier
	s_setprio 1
	s_waitcnt lgkmcnt(0)
	v_mfma_f32_16x16x32_bf16 v[60:63], v[120:123], v[160:163], v[60:63]
	v_mfma_f32_16x16x32_bf16 v[56:59], v[136:139], v[160:163], v[56:59]
	v_mfma_f32_16x16x32_bf16 v[44:47], v[120:123], v[184:187], v[44:47]
	v_mfma_f32_16x16x32_bf16 v[40:43], v[136:139], v[184:187], v[40:43]
	v_mfma_f32_16x16x32_bf16 v[28:31], v[120:123], v[192:195], v[28:31]
	v_mfma_f32_16x16x32_bf16 v[24:27], v[136:139], v[192:195], v[24:27]
	v_mfma_f32_16x16x32_bf16 v[12:15], v[120:123], v[200:203], v[12:15]
	v_mfma_f32_16x16x32_bf16 v[8:11], v[136:139], v[200:203], v[8:11]
	v_mfma_f32_16x16x32_bf16 v[60:63], v[128:131], v[164:167], v[60:63]
	v_mfma_f32_16x16x32_bf16 v[56:59], v[140:143], v[164:167], v[56:59]
	v_mfma_f32_16x16x32_bf16 v[44:47], v[128:131], v[188:191], v[44:47]
	v_mfma_f32_16x16x32_bf16 v[40:43], v[140:143], v[188:191], v[40:43]
	v_mfma_f32_16x16x32_bf16 v[28:31], v[128:131], v[196:199], v[28:31]
	v_mfma_f32_16x16x32_bf16 v[24:27], v[140:143], v[196:199], v[24:27]
	v_mfma_f32_16x16x32_bf16 v[12:15], v[128:131], v[216:219], v[12:15]
	v_mfma_f32_16x16x32_bf16 v[8:11], v[140:143], v[216:219], v[8:11]
	v_mfma_f32_16x16x32_bf16 v[52:55], v[144:147], v[160:163], v[52:55]
	v_mfma_f32_16x16x32_bf16 v[48:51], v[152:155], v[160:163], v[48:51]
	v_mfma_f32_16x16x32_bf16 v[36:39], v[144:147], v[184:187], v[36:39]
	v_mfma_f32_16x16x32_bf16 v[32:35], v[152:155], v[184:187], v[32:35]
	v_mfma_f32_16x16x32_bf16 v[20:23], v[144:147], v[192:195], v[20:23]
	v_mfma_f32_16x16x32_bf16 v[16:19], v[152:155], v[192:195], v[16:19]
	v_mfma_f32_16x16x32_bf16 v[4:7], v[144:147], v[200:203], v[4:7]
	v_mfma_f32_16x16x32_bf16 v[0:3], v[152:155], v[200:203], v[0:3]
	v_mfma_f32_16x16x32_bf16 v[52:55], v[148:151], v[164:167], v[52:55]
	v_mfma_f32_16x16x32_bf16 v[48:51], v[156:159], v[164:167], v[48:51]
	v_mfma_f32_16x16x32_bf16 v[36:39], v[148:151], v[188:191], v[36:39]
	v_mfma_f32_16x16x32_bf16 v[32:35], v[156:159], v[188:191], v[32:35]
	v_mfma_f32_16x16x32_bf16 v[20:23], v[148:151], v[196:199], v[20:23]
	v_mfma_f32_16x16x32_bf16 v[16:19], v[156:159], v[196:199], v[16:19]
	v_mfma_f32_16x16x32_bf16 v[4:7], v[148:151], v[216:219], v[4:7]
	v_mfma_f32_16x16x32_bf16 v[0:3], v[156:159], v[216:219], v[0:3]
	s_setprio 0
	s_barrier
	s_add_i32 s47, s47, 2
	s_add_u32 s21, s21, 0x100
	s_addc_u32 s46, s46, 0
	s_cmp_gt_u32 s47, 41
	s_mov_b64 s[22:23], s[4:5]
	s_cbranch_scc0 .LBB0_1325
	s_and_b64 vcc, exec, s[10:11]
	s_cbranch_vccz .LBB0_1328
	s_barrier
